# baseline (speedup 1.0000x reference)
; #define WAIT_V(n) asm volatile("s_waitcnt vmcnt(" #n ")" ::: "memory")
; #define WAIT_L(n) asm volatile("s_waitcnt lgkmcnt(" #n ")" ::: "memory")
; #define BAR __builtin_amdgcn_s_barrier()
; #define SCHED __builtin_amdgcn_sched_barrier(0)
; template <int MODE>
; __device__ __forceinline__ void gemm_tile(const int ph, const int which, const int pm, const int pn) {
;     ...
;   for (int t = 0; t < nt - 2; t += 2) {
;     LDB(B0, 0, 0); SCHED; LDA(At, 0, 0); STAGE(SA(1, 1), RA, brow + HALF, t + 1);
;     WAIT_L(8); BAR; WAIT_L(0); MMA(0, 0, At, B0); BAR; SCHED;
;     LDB(B1, 0, 1); STAGE(SB(0, 0), RB, bcol, t + 2);
;     BAR; WAIT_L(0); MMA(0, 1, At, B1); BAR;
;     LDA(At, 0, 1); STAGE(SA(0, 0), RA, brow, t + 2);
;     BAR; WAIT_L(0); MMA(1, 0, At, B0); BAR; SCHED;
;     STAGE(SB(0, 1), RB, bcolB, t + 2);
;     WAIT_V(6); BAR; MMA(1, 1, At, B1); BAR;
.LBB0_131:
	ds_read_b128 v[160:163], v158
	ds_read_b128 v[164:167], v158 offset:1024
	ds_read_b128 v[168:171], v158 offset:2048
	ds_read_b128 v[172:175], v158 offset:3072
	s_add_i32 s12, s16, s25
	v_readfirstlane_b32 s28, v155
	s_add_i32 s13, s12, 0x80
	s_mov_b32 m0, s28
	ds_read_b128 v[176:179], v137
	ds_read_b128 v[180:183], v137 offset:1024
	ds_read_b128 v[184:187], v136
	ds_read_b128 v[188:191], v136 offset:1024
	ds_read_b128 v[192:195], v135
	ds_read_b128 v[196:199], v135 offset:1024
	ds_read_b128 v[200:203], v134
	ds_read_b128 v[204:207], v134 offset:1024
	buffer_load_dwordx4 v138, s[4:7], s13 offen lds
	s_add_i32 s13, s3, s25
	v_readfirstlane_b32 s29, v153
	s_add_i32 s28, s13, 0x80
	s_mov_b32 m0, s29
	s_nop 0
	buffer_load_dwordx4 v138, s[4:7], s28 offen lds
	s_waitcnt lgkmcnt(8)
	s_barrier
	s_waitcnt lgkmcnt(0)
	s_setprio 1
	s_waitcnt lgkmcnt(7)
	v_mfma_f32_16x16x32_bf16 v[126:129], v[160:163], v[176:179], v[126:129]
	v_mfma_f32_16x16x32_bf16 v[122:125], v[168:171], v[176:179], v[122:125]
	s_waitcnt lgkmcnt(5)
	v_mfma_f32_16x16x32_bf16 v[118:121], v[160:163], v[184:187], v[118:121]
	v_mfma_f32_16x16x32_bf16 v[114:117], v[168:171], v[184:187], v[114:117]
	s_waitcnt lgkmcnt(3)
	v_mfma_f32_16x16x32_bf16 v[110:113], v[160:163], v[192:195], v[110:113]
	v_mfma_f32_16x16x32_bf16 v[106:109], v[168:171], v[192:195], v[106:109]
	s_waitcnt lgkmcnt(1)
	v_mfma_f32_16x16x32_bf16 v[102:105], v[160:163], v[200:203], v[102:105]
	v_mfma_f32_16x16x32_bf16 v[98:101], v[168:171], v[200:203], v[98:101]
	v_mfma_f32_16x16x32_bf16 v[126:129], v[164:167], v[180:183], v[126:129]
	v_mfma_f32_16x16x32_bf16 v[122:125], v[172:175], v[180:183], v[122:125]
	v_mfma_f32_16x16x32_bf16 v[118:121], v[164:167], v[188:191], v[118:121]
	v_mfma_f32_16x16x32_bf16 v[114:117], v[172:175], v[188:191], v[114:117]
	v_mfma_f32_16x16x32_bf16 v[110:113], v[164:167], v[196:199], v[110:113]
	v_mfma_f32_16x16x32_bf16 v[106:109], v[172:175], v[196:199], v[106:109]
	s_waitcnt lgkmcnt(0)
	v_mfma_f32_16x16x32_bf16 v[102:105], v[164:167], v[204:207], v[102:105]
	v_mfma_f32_16x16x32_bf16 v[98:101], v[172:175], v[204:207], v[98:101]
	s_setprio 0
	s_barrier
	s_add_i32 s28, s24, s25
	v_readfirstlane_b32 s38, v141
	s_add_i32 s29, s28, 0x100
	s_mov_b32 m0, s38
	ds_read_b128 v[236:239], v157
	ds_read_b128 v[240:243], v157 offset:1024
	ds_read_b128 v[244:247], v157 offset:2048
	ds_read_b128 v[248:251], v157 offset:3072
	buffer_load_dwordx4 v138, s[68:71], s29 offen lds
	s_add_i32 s29, s23, s25
	v_readfirstlane_b32 s43, v142
	s_add_i32 s38, s29, 0x100
	s_mov_b32 m0, s43
	s_add_i32 s27, s27, 2
	buffer_load_dwordx4 v138, s[68:71], s38 offen lds
	s_barrier
	s_waitcnt lgkmcnt(0)
	s_setprio 1
	s_waitcnt lgkmcnt(3)
	v_mfma_f32_16x16x32_bf16 v[94:97], v[236:239], v[176:179], v[94:97]
	s_waitcnt lgkmcnt(1)
	v_mfma_f32_16x16x32_bf16 v[90:93], v[244:247], v[176:179], v[90:93]
	v_mfma_f32_16x16x32_bf16 v[86:89], v[236:239], v[184:187], v[86:89]
	v_mfma_f32_16x16x32_bf16 v[82:85], v[244:247], v[184:187], v[82:85]
	v_mfma_f32_16x16x32_bf16 v[78:81], v[236:239], v[192:195], v[78:81]
	v_mfma_f32_16x16x32_bf16 v[74:77], v[244:247], v[192:195], v[74:77]
	v_mfma_f32_16x16x32_bf16 v[70:73], v[236:239], v[200:203], v[70:73]
	v_mfma_f32_16x16x32_bf16 v[66:69], v[244:247], v[200:203], v[66:69]
	v_mfma_f32_16x16x32_bf16 v[94:97], v[240:243], v[180:183], v[94:97]
	s_waitcnt lgkmcnt(0)
	v_mfma_f32_16x16x32_bf16 v[90:93], v[248:251], v[180:183], v[90:93]
	v_mfma_f32_16x16x32_bf16 v[86:89], v[240:243], v[188:191], v[86:89]
	v_mfma_f32_16x16x32_bf16 v[82:85], v[248:251], v[188:191], v[82:85]
	v_mfma_f32_16x16x32_bf16 v[78:81], v[240:243], v[196:199], v[78:81]
	v_mfma_f32_16x16x32_bf16 v[74:77], v[248:251], v[196:199], v[74:77]
	v_mfma_f32_16x16x32_bf16 v[70:73], v[240:243], v[204:207], v[70:73]
	v_mfma_f32_16x16x32_bf16 v[66:69], v[248:251], v[204:207], v[66:69]
	s_setprio 0
	s_add_i32 s38, s22, s25
	v_readfirstlane_b32 s50, v139
	s_add_i32 s43, s38, 0x100
	s_mov_b32 m0, s50
	s_barrier
	ds_read_b128 v[176:179], v137 offset:16384
	ds_read_b128 v[180:183], v137 offset:17408
	ds_read_b128 v[184:187], v136 offset:16384
	ds_read_b128 v[188:191], v136 offset:17408
	ds_read_b128 v[192:195], v135 offset:16384
	ds_read_b128 v[196:199], v135 offset:17408
	ds_read_b128 v[200:203], v134 offset:16384
	ds_read_b128 v[204:207], v134 offset:17408
	buffer_load_dwordx4 v138, s[4:7], s43 offen lds
	s_add_i32 s43, s19, s25
	v_readfirstlane_b32 s51, v143
	s_add_i32 s50, s43, 0x100
	s_mov_b32 m0, s51
	s_nop 0
	buffer_load_dwordx4 v138, s[4:7], s50 offen lds
	s_barrier
	s_waitcnt lgkmcnt(0)
	s_setprio 1
	s_waitcnt lgkmcnt(7)
	v_mfma_f32_16x16x32_bf16 v[62:65], v[160:163], v[176:179], v[62:65]
	v_mfma_f32_16x16x32_bf16 v[58:61], v[168:171], v[176:179], v[58:61]
	s_waitcnt lgkmcnt(5)
	v_mfma_f32_16x16x32_bf16 v[54:57], v[160:163], v[184:187], v[54:57]
	v_mfma_f32_16x16x32_bf16 v[50:53], v[168:171], v[184:187], v[50:53]
	s_waitcnt lgkmcnt(3)
	v_mfma_f32_16x16x32_bf16 v[46:49], v[160:163], v[192:195], v[46:49]
	v_mfma_f32_16x16x32_bf16 v[42:45], v[168:171], v[192:195], v[42:45]
	s_waitcnt lgkmcnt(1)
	v_mfma_f32_16x16x32_bf16 v[38:41], v[160:163], v[200:203], v[38:41]
	v_mfma_f32_16x16x32_bf16 v[34:37], v[168:171], v[200:203], v[34:37]
	v_mfma_f32_16x16x32_bf16 v[62:65], v[164:167], v[180:183], v[62:65]
	v_mfma_f32_16x16x32_bf16 v[58:61], v[172:175], v[180:183], v[58:61]
	v_mfma_f32_16x16x32_bf16 v[54:57], v[164:167], v[188:191], v[54:57]
	v_mfma_f32_16x16x32_bf16 v[50:53], v[172:175], v[188:191], v[50:53]
	v_mfma_f32_16x16x32_bf16 v[46:49], v[164:167], v[196:199], v[46:49]
	v_mfma_f32_16x16x32_bf16 v[42:45], v[172:175], v[196:199], v[42:45]
	s_waitcnt lgkmcnt(0)
	v_mfma_f32_16x16x32_bf16 v[38:41], v[164:167], v[204:207], v[38:41]
	v_mfma_f32_16x16x32_bf16 v[34:37], v[172:175], v[204:207], v[34:37]
	s_setprio 0
	s_barrier
; #define WAIT_V(n) asm volatile("s_waitcnt vmcnt(" #n ")" ::: "memory")
; #define WAIT_L(n) asm volatile("s_waitcnt lgkmcnt(" #n ")" ::: "memory")
; #define BAR __builtin_amdgcn_s_barrier()
; #define SCHED __builtin_amdgcn_sched_barrier(0)
; template <int MODE>
; __device__ __forceinline__ void gemm_tile(const int ph, const int which, const int pm, const int pn) {
;     ...
;     WAIT_V(6); BAR; MMA(1, 1, At, B1); BAR;
;     LDB(B0, 1, 0); SCHED; LDA(At, 1, 0); STAGE(SA(0, 1), RA, brow + HALF, t + 2);
;     WAIT_L(8); BAR; WAIT_L(0); MMA(0, 0, At, B0); BAR; SCHED;
;     LDB(B1, 1, 1); STAGE(SB(1, 0), RB, bcol, t + 3);
;     BAR; WAIT_L(0); MMA(0, 1, At, B1); BAR;
;     LDA(At, 1, 1); STAGE(SA(1, 0), RA, brow, t + 3);
;     BAR; WAIT_L(0); MMA(1, 0, At, B0); BAR; SCHED;
	s_add_i32 s50, s18, s25
	v_readfirstlane_b32 s72, v144
	s_add_i32 s51, s50, 0x100
	s_mov_b32 m0, s72
	v_readfirstlane_b32 s73, v145
	buffer_load_dwordx4 v138, s[68:71], s51 offen lds
	s_add_i32 s51, s17, s25
	s_add_i32 s72, s51, 0x100
	s_mov_b32 m0, s73
	s_nop 0
	buffer_load_dwordx4 v138, s[68:71], s72 offen lds
	s_waitcnt vmcnt(6)
	s_barrier
	s_setprio 1
	v_mfma_f32_16x16x32_bf16 v[30:33], v[236:239], v[176:179], v[30:33]
	v_mfma_f32_16x16x32_bf16 v[26:29], v[244:247], v[176:179], v[26:29]
	v_mfma_f32_16x16x32_bf16 v[22:25], v[236:239], v[184:187], v[22:25]
	v_mfma_f32_16x16x32_bf16 v[18:21], v[244:247], v[184:187], v[18:21]
	v_mfma_f32_16x16x32_bf16 v[14:17], v[236:239], v[192:195], v[14:17]
	v_mfma_f32_16x16x32_bf16 v[10:13], v[244:247], v[192:195], v[10:13]
	v_mfma_f32_16x16x32_bf16 v[6:9], v[236:239], v[200:203], v[6:9]
	v_mfma_f32_16x16x32_bf16 v[2:5], v[244:247], v[200:203], v[2:5]
	v_mfma_f32_16x16x32_bf16 v[30:33], v[240:243], v[180:183], v[30:33]
	v_mfma_f32_16x16x32_bf16 v[26:29], v[248:251], v[180:183], v[26:29]
	v_mfma_f32_16x16x32_bf16 v[22:25], v[240:243], v[188:191], v[22:25]
	v_mfma_f32_16x16x32_bf16 v[18:21], v[248:251], v[188:191], v[18:21]
	v_mfma_f32_16x16x32_bf16 v[14:17], v[240:243], v[196:199], v[14:17]
	v_mfma_f32_16x16x32_bf16 v[10:13], v[248:251], v[196:199], v[10:13]
	v_mfma_f32_16x16x32_bf16 v[6:9], v[240:243], v[204:207], v[6:9]
	v_mfma_f32_16x16x32_bf16 v[2:5], v[248:251], v[204:207], v[2:5]
	s_setprio 0
	s_barrier
	ds_read_b128 v[160:163], v146
	ds_read_b128 v[164:167], v146 offset:1024
	ds_read_b128 v[168:171], v146 offset:2048
	ds_read_b128 v[172:175], v146 offset:3072
	v_readfirstlane_b32 s72, v147
	s_addk_i32 s12, 0x100
	s_mov_b32 m0, s72
	ds_read_b128 v[176:179], v137 offset:32768
	ds_read_b128 v[180:183], v137 offset:33792
	ds_read_b128 v[184:187], v136 offset:32768
	ds_read_b128 v[188:191], v136 offset:33792
	ds_read_b128 v[192:195], v135 offset:32768
	ds_read_b128 v[196:199], v135 offset:33792
	ds_read_b128 v[200:203], v134 offset:32768
	ds_read_b128 v[204:207], v134 offset:33792
	buffer_load_dwordx4 v138, s[4:7], s12 offen lds
	v_readfirstlane_b32 s12, v148
	s_addk_i32 s13, 0x100
	s_mov_b32 m0, s12
	s_nop 0
	buffer_load_dwordx4 v138, s[4:7], s13 offen lds
	s_waitcnt lgkmcnt(8)
	s_barrier
	s_waitcnt lgkmcnt(0)
	s_setprio 1
	s_waitcnt lgkmcnt(7)
	v_mfma_f32_16x16x32_bf16 v[126:129], v[160:163], v[176:179], v[126:129]
	v_mfma_f32_16x16x32_bf16 v[122:125], v[168:171], v[176:179], v[122:125]
	s_waitcnt lgkmcnt(5)
	v_mfma_f32_16x16x32_bf16 v[118:121], v[160:163], v[184:187], v[118:121]
	v_mfma_f32_16x16x32_bf16 v[114:117], v[168:171], v[184:187], v[114:117]
	s_waitcnt lgkmcnt(3)
	v_mfma_f32_16x16x32_bf16 v[110:113], v[160:163], v[192:195], v[110:113]
	v_mfma_f32_16x16x32_bf16 v[106:109], v[168:171], v[192:195], v[106:109]
	s_waitcnt lgkmcnt(1)
	v_mfma_f32_16x16x32_bf16 v[102:105], v[160:163], v[200:203], v[102:105]
	v_mfma_f32_16x16x32_bf16 v[98:101], v[168:171], v[200:203], v[98:101]
	v_mfma_f32_16x16x32_bf16 v[126:129], v[164:167], v[180:183], v[126:129]
	v_mfma_f32_16x16x32_bf16 v[122:125], v[172:175], v[180:183], v[122:125]
	v_mfma_f32_16x16x32_bf16 v[118:121], v[164:167], v[188:191], v[118:121]
	v_mfma_f32_16x16x32_bf16 v[114:117], v[172:175], v[188:191], v[114:117]
	v_mfma_f32_16x16x32_bf16 v[110:113], v[164:167], v[196:199], v[110:113]
	v_mfma_f32_16x16x32_bf16 v[106:109], v[172:175], v[196:199], v[106:109]
	s_waitcnt lgkmcnt(0)
	v_mfma_f32_16x16x32_bf16 v[102:105], v[164:167], v[204:207], v[102:105]
	v_mfma_f32_16x16x32_bf16 v[98:101], v[172:175], v[204:207], v[98:101]
	s_setprio 0
	s_barrier
	v_readfirstlane_b32 s12, v149
	s_addk_i32 s28, 0x180
	s_mov_b32 m0, s12
	v_readfirstlane_b32 s12, v150
	ds_read_b128 v[236:239], v140
	ds_read_b128 v[240:243], v140 offset:1024
	ds_read_b128 v[244:247], v140 offset:2048
	ds_read_b128 v[248:251], v140 offset:3072
	buffer_load_dwordx4 v138, s[68:71], s28 offen lds
	s_addk_i32 s29, 0x180
	s_mov_b32 m0, s12
	s_nop 0
	buffer_load_dwordx4 v138, s[68:71], s29 offen lds
	s_barrier
	s_waitcnt lgkmcnt(0)
	s_setprio 1
	s_waitcnt lgkmcnt(3)
	v_mfma_f32_16x16x32_bf16 v[94:97], v[236:239], v[176:179], v[94:97]
	s_waitcnt lgkmcnt(1)
	v_mfma_f32_16x16x32_bf16 v[90:93], v[244:247], v[176:179], v[90:93]
	v_mfma_f32_16x16x32_bf16 v[86:89], v[236:239], v[184:187], v[86:89]
	v_mfma_f32_16x16x32_bf16 v[82:85], v[244:247], v[184:187], v[82:85]
	v_mfma_f32_16x16x32_bf16 v[78:81], v[236:239], v[192:195], v[78:81]
	v_mfma_f32_16x16x32_bf16 v[74:77], v[244:247], v[192:195], v[74:77]
	v_mfma_f32_16x16x32_bf16 v[70:73], v[236:239], v[200:203], v[70:73]
	v_mfma_f32_16x16x32_bf16 v[66:69], v[244:247], v[200:203], v[66:69]
	v_mfma_f32_16x16x32_bf16 v[94:97], v[240:243], v[180:183], v[94:97]
	s_waitcnt lgkmcnt(0)
	v_mfma_f32_16x16x32_bf16 v[90:93], v[248:251], v[180:183], v[90:93]
	v_mfma_f32_16x16x32_bf16 v[86:89], v[240:243], v[188:191], v[86:89]
	v_mfma_f32_16x16x32_bf16 v[82:85], v[248:251], v[188:191], v[82:85]
	v_mfma_f32_16x16x32_bf16 v[78:81], v[240:243], v[196:199], v[78:81]
	v_mfma_f32_16x16x32_bf16 v[74:77], v[248:251], v[196:199], v[74:77]
	v_mfma_f32_16x16x32_bf16 v[70:73], v[240:243], v[204:207], v[70:73]
	v_mfma_f32_16x16x32_bf16 v[66:69], v[248:251], v[204:207], v[66:69]
	s_setprio 0
	v_readfirstlane_b32 s12, v151
	s_addk_i32 s38, 0x180
	s_mov_b32 m0, s12
	v_readfirstlane_b32 s12, v152
	s_barrier
	ds_read_b128 v[176:179], v137 offset:49152
	ds_read_b128 v[180:183], v137 offset:50176
	ds_read_b128 v[184:187], v136 offset:49152
	ds_read_b128 v[188:191], v136 offset:50176
	ds_read_b128 v[192:195], v135 offset:49152
	ds_read_b128 v[196:199], v135 offset:50176
	ds_read_b128 v[200:203], v134 offset:49152
	ds_read_b128 v[204:207], v134 offset:50176
	buffer_load_dwordx4 v138, s[4:7], s38 offen lds
	s_addk_i32 s43, 0x180
	s_mov_b32 m0, s12
	s_nop 0
	buffer_load_dwordx4 v138, s[4:7], s43 offen lds
	s_barrier
; #define WAIT_V(n) asm volatile("s_waitcnt vmcnt(" #n ")" ::: "memory")
; #define WAIT_L(n) asm volatile("s_waitcnt lgkmcnt(" #n ")" ::: "memory")
; #define BAR __builtin_amdgcn_s_barrier()
; #define SCHED __builtin_amdgcn_sched_barrier(0)
; template <int MODE>
; __device__ __forceinline__ void gemm_tile(const int ph, const int which, const int pm, const int pn) {
;     ...
;     BAR; WAIT_L(0); MMA(1, 0, At, B0); BAR; SCHED;
;     STAGE(SB(1, 1), RB, bcolB, t + 3);
;     WAIT_V(6); BAR; MMA(1, 1, At, B1); BAR;
;   }
;   {
;     LDB(B0, 0, 0); LDA(At, 0, 0); STAGE(SA(1, 1), RA, brow + HALF, nt - 1);
;     BAR; WAIT_L(0); MMA(0, 0, At, B0); BAR;
;     LDB(B1, 0, 1); BAR; WAIT_L(0); MMA(0, 1, At, B1); BAR;
	s_waitcnt lgkmcnt(0)
	s_setprio 1
	s_waitcnt lgkmcnt(7)
	v_mfma_f32_16x16x32_bf16 v[62:65], v[160:163], v[176:179], v[62:65]
	v_mfma_f32_16x16x32_bf16 v[58:61], v[168:171], v[176:179], v[58:61]
	s_waitcnt lgkmcnt(5)
	v_mfma_f32_16x16x32_bf16 v[54:57], v[160:163], v[184:187], v[54:57]
	v_mfma_f32_16x16x32_bf16 v[50:53], v[168:171], v[184:187], v[50:53]
	s_waitcnt lgkmcnt(3)
	v_mfma_f32_16x16x32_bf16 v[46:49], v[160:163], v[192:195], v[46:49]
	v_mfma_f32_16x16x32_bf16 v[42:45], v[168:171], v[192:195], v[42:45]
	s_waitcnt lgkmcnt(1)
	v_mfma_f32_16x16x32_bf16 v[38:41], v[160:163], v[200:203], v[38:41]
	v_mfma_f32_16x16x32_bf16 v[34:37], v[168:171], v[200:203], v[34:37]
	v_mfma_f32_16x16x32_bf16 v[62:65], v[164:167], v[180:183], v[62:65]
	v_mfma_f32_16x16x32_bf16 v[58:61], v[172:175], v[180:183], v[58:61]
	v_mfma_f32_16x16x32_bf16 v[54:57], v[164:167], v[188:191], v[54:57]
	v_mfma_f32_16x16x32_bf16 v[50:53], v[172:175], v[188:191], v[50:53]
	v_mfma_f32_16x16x32_bf16 v[46:49], v[164:167], v[196:199], v[46:49]
	v_mfma_f32_16x16x32_bf16 v[42:45], v[172:175], v[196:199], v[42:45]
	s_waitcnt lgkmcnt(0)
	v_mfma_f32_16x16x32_bf16 v[38:41], v[164:167], v[204:207], v[38:41]
	v_mfma_f32_16x16x32_bf16 v[34:37], v[172:175], v[204:207], v[34:37]
	s_setprio 0
	s_barrier
	v_readfirstlane_b32 s12, v154
	s_addk_i32 s50, 0x180
	s_mov_b32 m0, s12
	v_readfirstlane_b32 s12, v156
	buffer_load_dwordx4 v138, s[68:71], s50 offen lds
	s_addk_i32 s51, 0x180
	s_mov_b32 m0, s12
	s_nop 0
	buffer_load_dwordx4 v138, s[68:71], s51 offen lds
	s_waitcnt vmcnt(6)
	s_barrier
	s_setprio 1
	v_mfma_f32_16x16x32_bf16 v[30:33], v[236:239], v[176:179], v[30:33]
	v_mfma_f32_16x16x32_bf16 v[26:29], v[244:247], v[176:179], v[26:29]
	v_mfma_f32_16x16x32_bf16 v[22:25], v[236:239], v[184:187], v[22:25]
	v_mfma_f32_16x16x32_bf16 v[18:21], v[244:247], v[184:187], v[18:21]
	v_mfma_f32_16x16x32_bf16 v[14:17], v[236:239], v[192:195], v[14:17]
	v_mfma_f32_16x16x32_bf16 v[10:13], v[244:247], v[192:195], v[10:13]
	v_mfma_f32_16x16x32_bf16 v[6:9], v[236:239], v[200:203], v[6:9]
	v_mfma_f32_16x16x32_bf16 v[2:5], v[244:247], v[200:203], v[2:5]
	v_mfma_f32_16x16x32_bf16 v[30:33], v[240:243], v[180:183], v[30:33]
	v_mfma_f32_16x16x32_bf16 v[26:29], v[248:251], v[180:183], v[26:29]
	v_mfma_f32_16x16x32_bf16 v[22:25], v[240:243], v[188:191], v[22:25]
	v_mfma_f32_16x16x32_bf16 v[18:21], v[248:251], v[188:191], v[18:21]
	v_mfma_f32_16x16x32_bf16 v[14:17], v[240:243], v[196:199], v[14:17]
	v_mfma_f32_16x16x32_bf16 v[10:13], v[248:251], v[196:199], v[10:13]
	v_mfma_f32_16x16x32_bf16 v[6:9], v[240:243], v[204:207], v[6:9]
	v_mfma_f32_16x16x32_bf16 v[2:5], v[248:251], v[204:207], v[2:5]
	s_setprio 0
	s_addk_i32 s25, 0x100
	s_cmp_lt_u32 s27, s2
	s_cbranch_scc1 .Lgemm_head_131
	s_barrier
	s_add_i32 s2, s26, s11
	s_lshl_b32 s2, s2, 1
	v_readfirstlane_b32 s3, v155
	s_addk_i32 s2, 0xff80
	s_mov_b32 s6, s70
	s_mov_b32 s7, s71
	s_mov_b32 m0, s3
	v_readfirstlane_b32 s3, v153
	ds_read_b128 v[142:145], v158
	ds_read_b128 v[148:151], v158 offset:1024
	ds_read_b128 v[160:163], v158 offset:2048
	ds_read_b128 v[164:167], v158 offset:3072
	ds_read_b128 v[168:171], v137
	ds_read_b128 v[172:175], v137 offset:1024
	ds_read_b128 v[176:179], v136
	ds_read_b128 v[180:183], v136 offset:1024
	ds_read_b128 v[184:187], v135
	ds_read_b128 v[188:191], v135 offset:1024
	ds_read_b128 v[192:195], v134
	ds_read_b128 v[196:199], v134 offset:1024
	buffer_load_dwordx4 v138, s[4:7], s2 offen lds
	s_add_i32 s2, s2, s10
	s_mov_b32 m0, s3
	s_nop 0
	buffer_load_dwordx4 v138, s[4:7], s2 offen lds
	s_barrier
	s_waitcnt lgkmcnt(0)
	s_setprio 1
	s_waitcnt lgkmcnt(7)
	v_mfma_f32_16x16x32_bf16 v[126:129], v[142:145], v[168:171], v[126:129]
	v_mfma_f32_16x16x32_bf16 v[122:125], v[160:163], v[168:171], v[122:125]
	s_waitcnt lgkmcnt(5)
	v_mfma_f32_16x16x32_bf16 v[118:121], v[142:145], v[176:179], v[118:121]
	v_mfma_f32_16x16x32_bf16 v[114:117], v[160:163], v[176:179], v[114:117]
	s_waitcnt lgkmcnt(1)
	v_mfma_f32_16x16x32_bf16 v[102:105], v[142:145], v[192:195], v[102:105]
	v_mfma_f32_16x16x32_bf16 v[98:101], v[160:163], v[192:195], v[98:101]
	v_mfma_f32_16x16x32_bf16 v[126:129], v[148:151], v[172:175], v[126:129]
	v_mfma_f32_16x16x32_bf16 v[122:125], v[164:167], v[172:175], v[122:125]
	v_mfma_f32_16x16x32_bf16 v[118:121], v[148:151], v[180:183], v[118:121]
	v_mfma_f32_16x16x32_bf16 v[114:117], v[164:167], v[180:183], v[114:117]
	v_mfma_f32_16x16x32_bf16 v[110:113], v[142:145], v[184:187], v[110:113]
	v_mfma_f32_16x16x32_bf16 v[106:109], v[160:163], v[184:187], v[106:109]
	s_waitcnt lgkmcnt(0)
	v_mfma_f32_16x16x32_bf16 v[102:105], v[148:151], v[196:199], v[102:105]
	v_mfma_f32_16x16x32_bf16 v[98:101], v[164:167], v[196:199], v[98:101]
	v_mfma_f32_16x16x32_bf16 v[152:155], v[148:151], v[188:191], v[110:113]
	v_mfma_f32_16x16x32_bf16 v[200:203], v[164:167], v[188:191], v[106:109]
	s_setprio 0
	s_barrier
	s_nop 0
	ds_read_b128 v[106:109], v157
	ds_read_b128 v[110:113], v157 offset:1024
	ds_read_b128 v[204:207], v157 offset:2048
	ds_read_b128 v[156:159], v157 offset:3072
	s_barrier
; #define WAIT_V(n) asm volatile("s_waitcnt vmcnt(" #n ")" ::: "memory")
; #define WAIT_L(n) asm volatile("s_waitcnt lgkmcnt(" #n ")" ::: "memory")
; #define BAR __builtin_amdgcn_s_barrier()
; template <int MODE>
; __device__ __forceinline__ void gemm_tile(const int ph, const int which, const int pm, const int pn) {
;     ...
;     LDB(B1, 0, 1); BAR; WAIT_L(0); MMA(0, 1, At, B1); BAR;
;     LDA(At, 0, 1); WAIT_V(4); BAR; WAIT_L(0); MMA(1, 0, At, B0); MMA(1, 1, At, B1); BAR;
;   }
;   {
;     LDB(B0, 1, 0); LDA(At, 1, 0); WAIT_V(2); BAR; WAIT_L(0); MMA(0, 0, At, B0); BAR;
	s_waitcnt lgkmcnt(0)
	s_setprio 1
	s_waitcnt lgkmcnt(3)
	v_mfma_f32_16x16x32_bf16 v[86:89], v[106:109], v[176:179], v[86:89]
	s_waitcnt lgkmcnt(1)
	v_mfma_f32_16x16x32_bf16 v[82:85], v[204:207], v[176:179], v[82:85]
	v_mfma_f32_16x16x32_bf16 v[70:73], v[106:109], v[192:195], v[70:73]
	v_mfma_f32_16x16x32_bf16 v[66:69], v[204:207], v[192:195], v[66:69]
	v_mfma_f32_16x16x32_bf16 v[94:97], v[106:109], v[168:171], v[94:97]
	v_mfma_f32_16x16x32_bf16 v[90:93], v[204:207], v[168:171], v[90:93]
	v_mfma_f32_16x16x32_bf16 v[86:89], v[110:113], v[180:183], v[86:89]
	s_waitcnt lgkmcnt(0)
	v_mfma_f32_16x16x32_bf16 v[82:85], v[156:159], v[180:183], v[82:85]
	v_mfma_f32_16x16x32_bf16 v[78:81], v[106:109], v[184:187], v[78:81]
	v_mfma_f32_16x16x32_bf16 v[74:77], v[204:207], v[184:187], v[74:77]
	v_mfma_f32_16x16x32_bf16 v[70:73], v[110:113], v[196:199], v[70:73]
	v_mfma_f32_16x16x32_bf16 v[66:69], v[156:159], v[196:199], v[66:69]
	v_mfma_f32_16x16x32_bf16 v[236:239], v[110:113], v[172:175], v[94:97]
	v_mfma_f32_16x16x32_bf16 v[168:171], v[156:159], v[172:175], v[90:93]
	v_mfma_f32_16x16x32_bf16 v[172:175], v[110:113], v[188:191], v[78:81]
	v_mfma_f32_16x16x32_bf16 v[176:179], v[156:159], v[188:191], v[74:77]
	s_setprio 0
	s_barrier
	s_nop 0
	ds_read_b128 v[74:77], v137 offset:16384
	ds_read_b128 v[78:81], v137 offset:17408
	ds_read_b128 v[90:93], v136 offset:16384
	ds_read_b128 v[94:97], v136 offset:17408
	ds_read_b128 v[180:183], v135 offset:16384
	ds_read_b128 v[184:187], v135 offset:17408
	ds_read_b128 v[188:191], v134 offset:16384
	ds_read_b128 v[192:195], v134 offset:17408
	s_waitcnt vmcnt(4)
	s_barrier
	s_waitcnt lgkmcnt(0)
	s_setprio 1
	s_waitcnt lgkmcnt(7)
	v_mfma_f32_16x16x32_bf16 v[62:65], v[142:145], v[74:77], v[62:65]
	v_mfma_f32_16x16x32_bf16 v[58:61], v[160:163], v[74:77], v[58:61]
	s_waitcnt lgkmcnt(5)
	v_mfma_f32_16x16x32_bf16 v[54:57], v[142:145], v[90:93], v[54:57]
	v_mfma_f32_16x16x32_bf16 v[50:53], v[160:163], v[90:93], v[50:53]
	s_waitcnt lgkmcnt(1)
	v_mfma_f32_16x16x32_bf16 v[38:41], v[142:145], v[188:191], v[38:41]
	v_mfma_f32_16x16x32_bf16 v[34:37], v[160:163], v[188:191], v[34:37]
	v_mfma_f32_16x16x32_bf16 v[62:65], v[148:151], v[78:81], v[62:65]
	v_mfma_f32_16x16x32_bf16 v[58:61], v[164:167], v[78:81], v[58:61]
	v_mfma_f32_16x16x32_bf16 v[54:57], v[148:151], v[94:97], v[54:57]
	v_mfma_f32_16x16x32_bf16 v[50:53], v[164:167], v[94:97], v[50:53]
	v_mfma_f32_16x16x32_bf16 v[46:49], v[142:145], v[180:183], v[46:49]
	v_mfma_f32_16x16x32_bf16 v[42:45], v[160:163], v[180:183], v[42:45]
	s_waitcnt lgkmcnt(0)
	v_mfma_f32_16x16x32_bf16 v[38:41], v[148:151], v[192:195], v[38:41]
	v_mfma_f32_16x16x32_bf16 v[34:37], v[164:167], v[192:195], v[34:37]
	v_mfma_f32_16x16x32_bf16 v[196:199], v[148:151], v[184:187], v[46:49]
	v_mfma_f32_16x16x32_bf16 v[240:243], v[164:167], v[184:187], v[42:45]
	s_setprio 0
	s_setprio 1
	v_mfma_f32_16x16x32_bf16 v[22:25], v[106:109], v[90:93], v[22:25]
	v_mfma_f32_16x16x32_bf16 v[18:21], v[204:207], v[90:93], v[18:21]
	v_mfma_f32_16x16x32_bf16 v[6:9], v[106:109], v[188:191], v[6:9]
	v_mfma_f32_16x16x32_bf16 v[2:5], v[204:207], v[188:191], v[2:5]
	v_mfma_f32_16x16x32_bf16 v[30:33], v[106:109], v[74:77], v[30:33]
	v_mfma_f32_16x16x32_bf16 v[26:29], v[204:207], v[74:77], v[26:29]
	v_mfma_f32_16x16x32_bf16 v[22:25], v[110:113], v[94:97], v[22:25]
	v_mfma_f32_16x16x32_bf16 v[18:21], v[156:159], v[94:97], v[18:21]
	v_mfma_f32_16x16x32_bf16 v[14:17], v[106:109], v[180:183], v[14:17]
	v_mfma_f32_16x16x32_bf16 v[10:13], v[204:207], v[180:183], v[10:13]
	v_mfma_f32_16x16x32_bf16 v[6:9], v[110:113], v[192:195], v[6:9]
	v_mfma_f32_16x16x32_bf16 v[2:5], v[156:159], v[192:195], v[2:5]
	v_mfma_f32_16x16x32_bf16 v[142:145], v[110:113], v[78:81], v[30:33]
	v_mfma_f32_16x16x32_bf16 v[148:151], v[156:159], v[78:81], v[26:29]
	v_mfma_f32_16x16x32_bf16 v[160:163], v[110:113], v[184:187], v[14:17]
	v_mfma_f32_16x16x32_bf16 v[164:167], v[156:159], v[184:187], v[10:13]
	s_setprio 0
	s_barrier
	s_nop 0
	ds_read_b128 v[10:13], v146
	ds_read_b128 v[14:17], v146 offset:1024
	ds_read_b128 v[156:159], v146 offset:2048
	ds_read_b128 v[180:183], v146 offset:3072
	ds_read_b128 v[26:29], v137 offset:32768
	ds_read_b128 v[30:33], v137 offset:33792
	ds_read_b128 v[42:45], v136 offset:32768
	ds_read_b128 v[46:49], v136 offset:33792
	ds_read_b128 v[184:187], v135 offset:32768
	ds_read_b128 v[188:191], v135 offset:33792
	ds_read_b128 v[192:195], v134 offset:32768
	ds_read_b128 v[204:207], v134 offset:33792
	s_waitcnt vmcnt(2)
	s_barrier
	s_waitcnt lgkmcnt(0)
	s_setprio 1
	s_waitcnt lgkmcnt(7)
	v_mfma_f32_16x16x32_bf16 v[74:77], v[10:13], v[26:29], v[126:129]
	s_waitcnt lgkmcnt(6)
	v_mfma_f32_16x16x32_bf16 v[126:129], v[14:17], v[30:33], v[74:77]
	v_mfma_f32_16x16x32_bf16 v[74:77], v[156:159], v[26:29], v[122:125]
	v_mfma_f32_16x16x32_bf16 v[122:125], v[180:183], v[30:33], v[74:77]
	s_waitcnt lgkmcnt(5)
	v_mfma_f32_16x16x32_bf16 v[74:77], v[10:13], v[42:45], v[118:121]
	s_waitcnt lgkmcnt(4)
	v_mfma_f32_16x16x32_bf16 v[110:113], v[14:17], v[46:49], v[74:77]
	v_mfma_f32_16x16x32_bf16 v[74:77], v[156:159], v[42:45], v[114:117]
	v_mfma_f32_16x16x32_bf16 v[106:109], v[180:183], v[46:49], v[74:77]
	s_waitcnt lgkmcnt(3)
	v_mfma_f32_16x16x32_bf16 v[74:77], v[10:13], v[184:187], v[152:155]
	s_waitcnt lgkmcnt(2)
	v_mfma_f32_16x16x32_bf16 v[94:97], v[14:17], v[188:191], v[74:77]
	v_mfma_f32_16x16x32_bf16 v[74:77], v[156:159], v[184:187], v[200:203]
	v_mfma_f32_16x16x32_bf16 v[90:93], v[180:183], v[188:191], v[74:77]
	s_waitcnt lgkmcnt(1)
	v_mfma_f32_16x16x32_bf16 v[74:77], v[10:13], v[192:195], v[102:105]
	s_waitcnt lgkmcnt(0)
	v_mfma_f32_16x16x32_bf16 v[78:81], v[14:17], v[204:207], v[74:77]
	v_mfma_f32_16x16x32_bf16 v[74:77], v[156:159], v[192:195], v[98:101]
	v_mfma_f32_16x16x32_bf16 v[74:77], v[180:183], v[204:207], v[74:77]
	s_setprio 0
	s_barrier
; #define WAIT_V(n) asm volatile("s_waitcnt vmcnt(" #n ")" ::: "memory")
; #define WAIT_L(n) asm volatile("s_waitcnt lgkmcnt(" #n ")" ::: "memory")
; #define BAR __builtin_amdgcn_s_barrier()
; template <int MODE>
; __device__ __forceinline__ void gemm_tile(const int ph, const int which, const int pm, const int pn) {
;     ...
;     LDB(B0, 1, 0); LDA(At, 1, 0); WAIT_V(2); BAR; WAIT_L(0); MMA(0, 0, At, B0); BAR;
;     LDB(B1, 1, 1); WAIT_V(0); BAR; WAIT_L(0); MMA(0, 1, At, B1); BAR;
;     LDA(At, 1, 1); BAR; WAIT_L(0); MMA(1, 0, At, B0); MMA(1, 1, At, B1); BAR;
;   }
;   if (wr == 0) BAR;
;   bf16_t* C; bf16_t* C2; const float* scale; const float* cw; const float* cb; int ldc, act, browC, ecol;
;   {
;     int ph2 = ph;
;     asm volatile("" : "+s"(ph2));
;     const Params p = load_params();
;     const GD g = make_gd(p, ph2, which);
;     TileP tp; TileE te;
;     tile_setup(g, pm, pn, tp, te);
;     C = te.C; C2 = te.C2; scale = te.scale; cw = te.cw; cb = te.cb; ldc = te.ldc; act = te.act; browC = te.browC; ecol = te.bcol;
;   }
	ds_read_b128 v[152:155], v140
	ds_read_b128 v[200:203], v140 offset:1024
	ds_read_b128 v[244:247], v140 offset:2048
	ds_read_b128 v[138:141], v140 offset:3072
	s_waitcnt vmcnt(0)
	s_barrier
	s_waitcnt lgkmcnt(0)
	s_setprio 1
	s_waitcnt lgkmcnt(3)
	v_mfma_f32_16x16x32_bf16 v[98:101], v[152:155], v[26:29], v[236:239]
	s_waitcnt lgkmcnt(1)
	v_mfma_f32_16x16x32_bf16 v[26:29], v[244:247], v[26:29], v[168:171]
	s_waitcnt lgkmcnt(0)
	v_mfma_f32_16x16x32_bf16 v[114:117], v[138:141], v[30:33], v[26:29]
	v_mfma_f32_16x16x32_bf16 v[26:29], v[152:155], v[42:45], v[86:89]
	v_mfma_f32_16x16x32_bf16 v[102:105], v[200:203], v[46:49], v[26:29]
	v_mfma_f32_16x16x32_bf16 v[26:29], v[244:247], v[42:45], v[82:85]
	v_mfma_f32_16x16x32_bf16 v[118:121], v[200:203], v[30:33], v[98:101]
	v_mfma_f32_16x16x32_bf16 v[98:101], v[138:141], v[46:49], v[26:29]
	v_mfma_f32_16x16x32_bf16 v[26:29], v[152:155], v[184:187], v[172:175]
	v_mfma_f32_16x16x32_bf16 v[86:89], v[200:203], v[188:191], v[26:29]
	v_mfma_f32_16x16x32_bf16 v[26:29], v[244:247], v[184:187], v[176:179]
	v_mfma_f32_16x16x32_bf16 v[82:85], v[138:141], v[188:191], v[26:29]
	v_mfma_f32_16x16x32_bf16 v[26:29], v[152:155], v[192:195], v[70:73]
	v_mfma_f32_16x16x32_bf16 v[70:73], v[200:203], v[204:207], v[26:29]
	v_mfma_f32_16x16x32_bf16 v[26:29], v[244:247], v[192:195], v[66:69]
	v_mfma_f32_16x16x32_bf16 v[66:69], v[138:141], v[204:207], v[26:29]
	s_setprio 0
	s_barrier
	ds_read_b128 v[168:171], v137 offset:49152
	ds_read_b128 v[172:175], v137 offset:50176
	ds_read_b128 v[176:179], v136 offset:49152
	ds_read_b128 v[184:187], v136 offset:50176
	ds_read_b128 v[188:191], v135 offset:49152
	ds_read_b128 v[192:195], v135 offset:50176
	ds_read_b128 v[204:207], v134 offset:49152
	ds_read_b128 v[134:137], v134 offset:50176
	s_barrier
	s_waitcnt lgkmcnt(0)
	s_setprio 1
	s_waitcnt lgkmcnt(7)
	v_mfma_f32_16x16x32_bf16 v[26:29], v[10:13], v[168:171], v[62:65]
	s_waitcnt lgkmcnt(6)
	v_mfma_f32_16x16x32_bf16 v[62:65], v[14:17], v[172:175], v[26:29]
	v_mfma_f32_16x16x32_bf16 v[26:29], v[156:159], v[168:171], v[58:61]
	v_mfma_f32_16x16x32_bf16 v[58:61], v[180:183], v[172:175], v[26:29]
	s_waitcnt lgkmcnt(5)
	v_mfma_f32_16x16x32_bf16 v[26:29], v[10:13], v[176:179], v[54:57]
	s_waitcnt lgkmcnt(4)
	v_mfma_f32_16x16x32_bf16 v[46:49], v[14:17], v[184:187], v[26:29]
	v_mfma_f32_16x16x32_bf16 v[26:29], v[156:159], v[176:179], v[50:53]
	v_mfma_f32_16x16x32_bf16 v[42:45], v[180:183], v[184:187], v[26:29]
	s_waitcnt lgkmcnt(3)
	v_mfma_f32_16x16x32_bf16 v[26:29], v[10:13], v[188:191], v[196:199]
	s_waitcnt lgkmcnt(1)
	v_mfma_f32_16x16x32_bf16 v[10:13], v[10:13], v[204:207], v[38:41]
	v_mfma_f32_16x16x32_bf16 v[30:33], v[14:17], v[192:195], v[26:29]
	v_mfma_f32_16x16x32_bf16 v[26:29], v[156:159], v[188:191], v[240:243]
	s_waitcnt lgkmcnt(0)
	v_mfma_f32_16x16x32_bf16 v[14:17], v[14:17], v[134:137], v[10:13]
	v_mfma_f32_16x16x32_bf16 v[10:13], v[156:159], v[204:207], v[34:37]
	v_mfma_f32_16x16x32_bf16 v[26:29], v[180:183], v[192:195], v[26:29]
	v_mfma_f32_16x16x32_bf16 v[10:13], v[180:183], v[134:137], v[10:13]
	s_setprio 0
	s_setprio 1
	v_mfma_f32_16x16x32_bf16 v[34:37], v[152:155], v[168:171], v[142:145]
	v_mfma_f32_16x16x32_bf16 v[54:57], v[200:203], v[172:175], v[34:37]
	v_mfma_f32_16x16x32_bf16 v[34:37], v[244:247], v[168:171], v[148:151]
	v_mfma_f32_16x16x32_bf16 v[18:21], v[244:247], v[176:179], v[18:21]
	v_mfma_f32_16x16x32_bf16 v[50:53], v[138:141], v[172:175], v[34:37]
	v_mfma_f32_16x16x32_bf16 v[22:25], v[152:155], v[176:179], v[22:25]
	v_mfma_f32_16x16x32_bf16 v[34:37], v[138:141], v[184:187], v[18:21]
	v_mfma_f32_16x16x32_bf16 v[18:21], v[152:155], v[188:191], v[160:163]
	v_mfma_f32_16x16x32_bf16 v[38:41], v[200:203], v[184:187], v[22:25]
	v_mfma_f32_16x16x32_bf16 v[22:25], v[200:203], v[192:195], v[18:21]
	v_mfma_f32_16x16x32_bf16 v[18:21], v[244:247], v[188:191], v[164:167]
	v_mfma_f32_16x16x32_bf16 v[6:9], v[152:155], v[204:207], v[6:9]
	v_mfma_f32_16x16x32_bf16 v[2:5], v[244:247], v[204:207], v[2:5]
	v_mfma_f32_16x16x32_bf16 v[18:21], v[138:141], v[192:195], v[18:21]
	v_mfma_f32_16x16x32_bf16 v[6:9], v[200:203], v[134:137], v[6:9]
	v_mfma_f32_16x16x32_bf16 v[2:5], v[138:141], v[134:137], v[2:5]
	s_setprio 0
	s_load_dwordx4 s[4:7], s[0:1], 0xf0
	s_movk_i32 s2, 0x100
	v_cmp_gt_u32_e32 vcc, s2, v0
	s_barrier
	s_and_saveexec_b64 s[2:3], vcc
	s_cbranch_execz .LBB0_134
	s_barrier
.LBB0_134:
	s_or_b64 exec, exec, s[2:3]
	s_mov_b32 s25, s34
	s_mov_b64 s[2:3], s[0:1]
	s_mov_b64 s[72:73], s[48:49]
	s_mov_b64 s[16:17], -1
	s_mov_b64 s[18:19], 0
	s_mov_b64 s[10:11], 0
	s_waitcnt lgkmcnt(0)
	s_add_u32 s2, s6, 0x3be6000
	s_addc_u32 s3, s7, 0
	s_add_u32 s23, s6, 0xe1a6000
	s_addc_u32 s24, s7, 0
	s_cmp_lt_i32 s25, 3
	s_cbranch_scc1 .LBB0_143
	s_cmp_gt_i32 s25, 16
	s_cbranch_scc0 .LBB0_137
	s_cmp_lg_u32 s25, 17
	s_mov_b64 s[16:17], 0
	s_cselect_b64 s[10:11], -1, 0

; #define WAIT_V(n) asm volatile("s_waitcnt vmcnt(" #n ")" ::: "memory")
; #define WAIT_L(n) asm volatile("s_waitcnt lgkmcnt(" #n ")" ::: "memory")
; #define BAR __builtin_amdgcn_s_barrier()
; #define SCHED __builtin_amdgcn_sched_barrier(0)
; template <int MODE>
; __device__ __forceinline__ void gemm_tile(const int ph, const int which, const int pm, const int pn) {
;     ...
;   for (int t = 0; t < nt - 2; t += 2) {
;     LDB(B0, 0, 0); SCHED; LDA(At, 0, 0); STAGE(SA(1, 1), RA, brow + HALF, t + 1);
;     WAIT_L(8); BAR; WAIT_L(0); MMA(0, 0, At, B0); BAR; SCHED;
;     LDB(B1, 0, 1); STAGE(SB(0, 0), RB, bcol, t + 2);
;     BAR; WAIT_L(0); MMA(0, 1, At, B1); BAR;
;     LDA(At, 0, 1); STAGE(SA(0, 0), RA, brow, t + 2);
;     BAR; WAIT_L(0); MMA(1, 0, At, B0); BAR; SCHED;
;     STAGE(SB(0, 1), RB, bcolB, t + 2);
;     WAIT_V(6); BAR; MMA(1, 1, At, B1); BAR;
.LBB0_370:
	ds_read_b128 v[156:159], v154
	ds_read_b128 v[168:171], v154 offset:1024
	ds_read_b128 v[172:175], v154 offset:2048
	ds_read_b128 v[176:179], v154 offset:3072
	s_add_i32 s12, s10, s21
	v_readfirstlane_b32 s23, v151
	s_add_i32 s13, s12, 0x80
	s_mov_b32 m0, s23
	ds_read_b128 v[180:183], v141
	ds_read_b128 v[184:187], v141 offset:1024
	ds_read_b128 v[188:191], v140
	ds_read_b128 v[192:195], v140 offset:1024
	ds_read_b128 v[196:199], v139
	ds_read_b128 v[200:203], v139 offset:1024
	ds_read_b128 v[204:207], v138
	ds_read_b128 v[236:239], v138 offset:1024
	buffer_load_dwordx4 v130, s[4:7], s13 offen lds
	s_add_i32 s13, s3, s21
	v_readfirstlane_b32 s27, v149
	s_add_i32 s23, s13, 0x80
	s_mov_b32 m0, s27
	s_nop 0
	buffer_load_dwordx4 v130, s[4:7], s23 offen lds
	s_waitcnt lgkmcnt(8)
	s_barrier
	s_waitcnt lgkmcnt(0)
	s_setprio 1
	s_waitcnt lgkmcnt(7)
	v_mfma_f32_16x16x32_bf16 v[2:5], v[156:159], v[180:183], v[2:5]
	v_mfma_f32_16x16x32_bf16 v[6:9], v[172:175], v[180:183], v[6:9]
	s_waitcnt lgkmcnt(5)
	v_mfma_f32_16x16x32_bf16 v[18:21], v[156:159], v[188:191], v[18:21]
	v_mfma_f32_16x16x32_bf16 v[30:33], v[172:175], v[188:191], v[30:33]
	s_waitcnt lgkmcnt(3)
	v_mfma_f32_16x16x32_bf16 v[42:45], v[156:159], v[196:199], v[42:45]
	v_mfma_f32_16x16x32_bf16 v[54:57], v[172:175], v[196:199], v[54:57]
	s_waitcnt lgkmcnt(1)
	v_mfma_f32_16x16x32_bf16 v[66:69], v[156:159], v[204:207], v[66:69]
	v_mfma_f32_16x16x32_bf16 v[78:81], v[172:175], v[204:207], v[78:81]
	v_mfma_f32_16x16x32_bf16 v[2:5], v[168:171], v[184:187], v[2:5]
	v_mfma_f32_16x16x32_bf16 v[6:9], v[176:179], v[184:187], v[6:9]
	v_mfma_f32_16x16x32_bf16 v[18:21], v[168:171], v[192:195], v[18:21]
	v_mfma_f32_16x16x32_bf16 v[30:33], v[176:179], v[192:195], v[30:33]
	v_mfma_f32_16x16x32_bf16 v[42:45], v[168:171], v[200:203], v[42:45]
	v_mfma_f32_16x16x32_bf16 v[54:57], v[176:179], v[200:203], v[54:57]
	s_waitcnt lgkmcnt(0)
	v_mfma_f32_16x16x32_bf16 v[66:69], v[168:171], v[236:239], v[66:69]
	v_mfma_f32_16x16x32_bf16 v[78:81], v[176:179], v[236:239], v[78:81]
	s_setprio 0
	s_barrier
	s_add_i32 s23, s20, s21
	v_readfirstlane_b32 s28, v132
	s_add_i32 s27, s23, 0x100
	s_mov_b32 m0, s28
	ds_read_b128 v[240:243], v153
	ds_read_b128 v[244:247], v153 offset:1024
	ds_read_b128 v[248:251], v153 offset:2048
	ds_read_b128 v[210:213], v153 offset:3072
	buffer_load_dwordx4 v130, s[68:71], s27 offen lds
	s_add_i32 s27, s19, s21
	v_readfirstlane_b32 s29, v133
	s_add_i32 s28, s27, 0x100
	s_mov_b32 m0, s29
	s_add_i32 s22, s22, 2
	buffer_load_dwordx4 v130, s[68:71], s28 offen lds
	s_barrier
	s_waitcnt lgkmcnt(0)
	s_setprio 1
	s_waitcnt lgkmcnt(3)
	v_mfma_f32_16x16x32_bf16 v[10:13], v[240:243], v[180:183], v[10:13]
	s_waitcnt lgkmcnt(1)
	v_mfma_f32_16x16x32_bf16 v[22:25], v[248:251], v[180:183], v[22:25]
	v_mfma_f32_16x16x32_bf16 v[34:37], v[240:243], v[188:191], v[34:37]
	v_mfma_f32_16x16x32_bf16 v[46:49], v[248:251], v[188:191], v[46:49]
	v_mfma_f32_16x16x32_bf16 v[58:61], v[240:243], v[196:199], v[58:61]
	v_mfma_f32_16x16x32_bf16 v[70:73], v[248:251], v[196:199], v[70:73]
	v_mfma_f32_16x16x32_bf16 v[82:85], v[240:243], v[204:207], v[82:85]
	v_mfma_f32_16x16x32_bf16 v[94:97], v[248:251], v[204:207], v[94:97]
	v_mfma_f32_16x16x32_bf16 v[10:13], v[244:247], v[184:187], v[10:13]
	s_waitcnt lgkmcnt(0)
	v_mfma_f32_16x16x32_bf16 v[22:25], v[210:213], v[184:187], v[22:25]
	v_mfma_f32_16x16x32_bf16 v[34:37], v[244:247], v[192:195], v[34:37]
	v_mfma_f32_16x16x32_bf16 v[46:49], v[210:213], v[192:195], v[46:49]
	v_mfma_f32_16x16x32_bf16 v[58:61], v[244:247], v[200:203], v[58:61]
	v_mfma_f32_16x16x32_bf16 v[70:73], v[210:213], v[200:203], v[70:73]
	v_mfma_f32_16x16x32_bf16 v[82:85], v[244:247], v[236:239], v[82:85]
	v_mfma_f32_16x16x32_bf16 v[94:97], v[210:213], v[236:239], v[94:97]
	s_setprio 0
	s_add_i32 s28, s18, s21
	v_readfirstlane_b32 s38, v131
	s_add_i32 s29, s28, 0x100
	s_mov_b32 m0, s38
	s_barrier
	ds_read_b128 v[180:183], v141 offset:16384
	ds_read_b128 v[184:187], v141 offset:17408
	ds_read_b128 v[188:191], v140 offset:16384
	ds_read_b128 v[192:195], v140 offset:17408
	ds_read_b128 v[196:199], v139 offset:16384
	ds_read_b128 v[200:203], v139 offset:17408
	ds_read_b128 v[204:207], v138 offset:16384
	ds_read_b128 v[236:239], v138 offset:17408
	buffer_load_dwordx4 v130, s[4:7], s29 offen lds
	s_add_i32 s29, s17, s21
	v_readfirstlane_b32 s43, v134
	s_add_i32 s38, s29, 0x100
	s_mov_b32 m0, s43
	s_nop 0
	buffer_load_dwordx4 v130, s[4:7], s38 offen lds
	s_barrier
	s_waitcnt lgkmcnt(0)
	s_setprio 1
	s_waitcnt lgkmcnt(7)
	v_mfma_f32_16x16x32_bf16 v[14:17], v[156:159], v[180:183], v[14:17]
	v_mfma_f32_16x16x32_bf16 v[26:29], v[172:175], v[180:183], v[26:29]
	s_waitcnt lgkmcnt(5)
	v_mfma_f32_16x16x32_bf16 v[38:41], v[156:159], v[188:191], v[38:41]
	v_mfma_f32_16x16x32_bf16 v[50:53], v[172:175], v[188:191], v[50:53]
	s_waitcnt lgkmcnt(3)
	v_mfma_f32_16x16x32_bf16 v[62:65], v[156:159], v[196:199], v[62:65]
	v_mfma_f32_16x16x32_bf16 v[74:77], v[172:175], v[196:199], v[74:77]
	s_waitcnt lgkmcnt(1)
	v_mfma_f32_16x16x32_bf16 v[86:89], v[156:159], v[204:207], v[86:89]
	v_mfma_f32_16x16x32_bf16 v[98:101], v[172:175], v[204:207], v[98:101]
	v_mfma_f32_16x16x32_bf16 v[14:17], v[168:171], v[184:187], v[14:17]
	v_mfma_f32_16x16x32_bf16 v[26:29], v[176:179], v[184:187], v[26:29]
	v_mfma_f32_16x16x32_bf16 v[38:41], v[168:171], v[192:195], v[38:41]
	v_mfma_f32_16x16x32_bf16 v[50:53], v[176:179], v[192:195], v[50:53]
	v_mfma_f32_16x16x32_bf16 v[62:65], v[168:171], v[200:203], v[62:65]
	v_mfma_f32_16x16x32_bf16 v[74:77], v[176:179], v[200:203], v[74:77]
	s_waitcnt lgkmcnt(0)
	v_mfma_f32_16x16x32_bf16 v[86:89], v[168:171], v[236:239], v[86:89]
	v_mfma_f32_16x16x32_bf16 v[98:101], v[176:179], v[236:239], v[98:101]
	s_setprio 0
	s_barrier
; #define WAIT_V(n) asm volatile("s_waitcnt vmcnt(" #n ")" ::: "memory")
; #define WAIT_L(n) asm volatile("s_waitcnt lgkmcnt(" #n ")" ::: "memory")
; #define BAR __builtin_amdgcn_s_barrier()
; #define SCHED __builtin_amdgcn_sched_barrier(0)
; template <int MODE>
; __device__ __forceinline__ void gemm_tile(const int ph, const int which, const int pm, const int pn) {
;     ...
;     WAIT_V(6); BAR; MMA(1, 1, At, B1); BAR;
;     LDB(B0, 1, 0); SCHED; LDA(At, 1, 0); STAGE(SA(0, 1), RA, brow + HALF, t + 2);
;     WAIT_L(8); BAR; WAIT_L(0); MMA(0, 0, At, B0); BAR; SCHED;
;     LDB(B1, 1, 1); STAGE(SB(1, 0), RB, bcol, t + 3);
;     BAR; WAIT_L(0); MMA(0, 1, At, B1); BAR;
;     LDA(At, 1, 1); STAGE(SA(1, 0), RA, brow, t + 3);
;     BAR; WAIT_L(0); MMA(1, 0, At, B0); BAR; SCHED;
	s_add_i32 s38, s16, s21
	v_readfirstlane_b32 s50, v135
	s_add_i32 s43, s38, 0x100
	s_mov_b32 m0, s50
	v_readfirstlane_b32 s51, v136
	buffer_load_dwordx4 v130, s[68:71], s43 offen lds
	s_add_i32 s43, s11, s21
	s_add_i32 s50, s43, 0x100
	s_mov_b32 m0, s51
	s_nop 0
	buffer_load_dwordx4 v130, s[68:71], s50 offen lds
	s_waitcnt vmcnt(6)
	s_barrier
	s_setprio 1
	v_mfma_f32_16x16x32_bf16 v[90:93], v[240:243], v[180:183], v[90:93]
	v_mfma_f32_16x16x32_bf16 v[102:105], v[248:251], v[180:183], v[102:105]
	v_mfma_f32_16x16x32_bf16 v[106:109], v[240:243], v[188:191], v[106:109]
	v_mfma_f32_16x16x32_bf16 v[110:113], v[248:251], v[188:191], v[110:113]
	v_mfma_f32_16x16x32_bf16 v[114:117], v[240:243], v[196:199], v[114:117]
	v_mfma_f32_16x16x32_bf16 v[118:121], v[248:251], v[196:199], v[118:121]
	v_mfma_f32_16x16x32_bf16 v[122:125], v[240:243], v[204:207], v[122:125]
	v_mfma_f32_16x16x32_bf16 v[126:129], v[248:251], v[204:207], v[126:129]
	v_mfma_f32_16x16x32_bf16 v[90:93], v[244:247], v[184:187], v[90:93]
	v_mfma_f32_16x16x32_bf16 v[102:105], v[210:213], v[184:187], v[102:105]
	v_mfma_f32_16x16x32_bf16 v[106:109], v[244:247], v[192:195], v[106:109]
	v_mfma_f32_16x16x32_bf16 v[110:113], v[210:213], v[192:195], v[110:113]
	v_mfma_f32_16x16x32_bf16 v[114:117], v[244:247], v[200:203], v[114:117]
	v_mfma_f32_16x16x32_bf16 v[118:121], v[210:213], v[200:203], v[118:121]
	v_mfma_f32_16x16x32_bf16 v[122:125], v[244:247], v[236:239], v[122:125]
	v_mfma_f32_16x16x32_bf16 v[126:129], v[210:213], v[236:239], v[126:129]
	s_setprio 0
	s_barrier
	ds_read_b128 v[156:159], v137
	ds_read_b128 v[168:171], v137 offset:1024
	ds_read_b128 v[172:175], v137 offset:2048
	ds_read_b128 v[176:179], v137 offset:3072
	v_readfirstlane_b32 s50, v143
	s_addk_i32 s12, 0x100
	s_mov_b32 m0, s50
	ds_read_b128 v[180:183], v141 offset:32768
	ds_read_b128 v[184:187], v141 offset:33792
	ds_read_b128 v[188:191], v140 offset:32768
	ds_read_b128 v[192:195], v140 offset:33792
	ds_read_b128 v[196:199], v139 offset:32768
	ds_read_b128 v[200:203], v139 offset:33792
	ds_read_b128 v[204:207], v138 offset:32768
	ds_read_b128 v[210:213], v138 offset:33792
	buffer_load_dwordx4 v130, s[4:7], s12 offen lds
	v_readfirstlane_b32 s12, v144
	s_addk_i32 s13, 0x100
	s_mov_b32 m0, s12
	s_nop 0
	buffer_load_dwordx4 v130, s[4:7], s13 offen lds
	s_waitcnt lgkmcnt(8)
	s_barrier
	s_waitcnt lgkmcnt(0)
	s_setprio 1
	s_waitcnt lgkmcnt(7)
	v_mfma_f32_16x16x32_bf16 v[2:5], v[156:159], v[180:183], v[2:5]
	v_mfma_f32_16x16x32_bf16 v[6:9], v[172:175], v[180:183], v[6:9]
	s_waitcnt lgkmcnt(5)
	v_mfma_f32_16x16x32_bf16 v[18:21], v[156:159], v[188:191], v[18:21]
	v_mfma_f32_16x16x32_bf16 v[30:33], v[172:175], v[188:191], v[30:33]
	s_waitcnt lgkmcnt(3)
	v_mfma_f32_16x16x32_bf16 v[42:45], v[156:159], v[196:199], v[42:45]
	v_mfma_f32_16x16x32_bf16 v[54:57], v[172:175], v[196:199], v[54:57]
	s_waitcnt lgkmcnt(1)
	v_mfma_f32_16x16x32_bf16 v[66:69], v[156:159], v[204:207], v[66:69]
	v_mfma_f32_16x16x32_bf16 v[78:81], v[172:175], v[204:207], v[78:81]
	v_mfma_f32_16x16x32_bf16 v[2:5], v[168:171], v[184:187], v[2:5]
	v_mfma_f32_16x16x32_bf16 v[6:9], v[176:179], v[184:187], v[6:9]
	v_mfma_f32_16x16x32_bf16 v[18:21], v[168:171], v[192:195], v[18:21]
	v_mfma_f32_16x16x32_bf16 v[30:33], v[176:179], v[192:195], v[30:33]
	v_mfma_f32_16x16x32_bf16 v[42:45], v[168:171], v[200:203], v[42:45]
	v_mfma_f32_16x16x32_bf16 v[54:57], v[176:179], v[200:203], v[54:57]
	s_waitcnt lgkmcnt(0)
	v_mfma_f32_16x16x32_bf16 v[66:69], v[168:171], v[210:213], v[66:69]
	v_mfma_f32_16x16x32_bf16 v[78:81], v[176:179], v[210:213], v[78:81]
	s_setprio 0
	s_barrier
	v_readfirstlane_b32 s12, v145
	s_addk_i32 s23, 0x180
	s_mov_b32 m0, s12
	v_readfirstlane_b32 s12, v146
	ds_read_b128 v[236:239], v142
	ds_read_b128 v[240:243], v142 offset:1024
	ds_read_b128 v[244:247], v142 offset:2048
	ds_read_b128 v[248:251], v142 offset:3072
	buffer_load_dwordx4 v130, s[68:71], s23 offen lds
	s_addk_i32 s27, 0x180
	s_mov_b32 m0, s12
	s_nop 0
	buffer_load_dwordx4 v130, s[68:71], s27 offen lds
	s_barrier
	s_waitcnt lgkmcnt(0)
	s_setprio 1
	s_waitcnt lgkmcnt(3)
	v_mfma_f32_16x16x32_bf16 v[10:13], v[236:239], v[180:183], v[10:13]
	s_waitcnt lgkmcnt(1)
	v_mfma_f32_16x16x32_bf16 v[22:25], v[244:247], v[180:183], v[22:25]
	v_mfma_f32_16x16x32_bf16 v[34:37], v[236:239], v[188:191], v[34:37]
	v_mfma_f32_16x16x32_bf16 v[46:49], v[244:247], v[188:191], v[46:49]
	v_mfma_f32_16x16x32_bf16 v[58:61], v[236:239], v[196:199], v[58:61]
	v_mfma_f32_16x16x32_bf16 v[70:73], v[244:247], v[196:199], v[70:73]
	v_mfma_f32_16x16x32_bf16 v[82:85], v[236:239], v[204:207], v[82:85]
	v_mfma_f32_16x16x32_bf16 v[94:97], v[244:247], v[204:207], v[94:97]
	v_mfma_f32_16x16x32_bf16 v[10:13], v[240:243], v[184:187], v[10:13]
	s_waitcnt lgkmcnt(0)
	v_mfma_f32_16x16x32_bf16 v[22:25], v[248:251], v[184:187], v[22:25]
	v_mfma_f32_16x16x32_bf16 v[34:37], v[240:243], v[192:195], v[34:37]
	v_mfma_f32_16x16x32_bf16 v[46:49], v[248:251], v[192:195], v[46:49]
	v_mfma_f32_16x16x32_bf16 v[58:61], v[240:243], v[200:203], v[58:61]
	v_mfma_f32_16x16x32_bf16 v[70:73], v[248:251], v[200:203], v[70:73]
	v_mfma_f32_16x16x32_bf16 v[82:85], v[240:243], v[210:213], v[82:85]
	v_mfma_f32_16x16x32_bf16 v[94:97], v[248:251], v[210:213], v[94:97]
	s_setprio 0
	v_readfirstlane_b32 s12, v147
	s_addk_i32 s28, 0x180
	s_mov_b32 m0, s12
	v_readfirstlane_b32 s12, v148
	s_barrier
	ds_read_b128 v[180:183], v141 offset:49152
	ds_read_b128 v[184:187], v141 offset:50176
	ds_read_b128 v[188:191], v140 offset:49152
	ds_read_b128 v[192:195], v140 offset:50176
	ds_read_b128 v[196:199], v139 offset:49152
	ds_read_b128 v[200:203], v139 offset:50176
	ds_read_b128 v[204:207], v138 offset:49152
	ds_read_b128 v[210:213], v138 offset:50176
	buffer_load_dwordx4 v130, s[4:7], s28 offen lds
	s_addk_i32 s29, 0x180
	s_mov_b32 m0, s12
	s_nop 0
	buffer_load_dwordx4 v130, s[4:7], s29 offen lds
	s_barrier
; #define WAIT_V(n) asm volatile("s_waitcnt vmcnt(" #n ")" ::: "memory")
; #define WAIT_L(n) asm volatile("s_waitcnt lgkmcnt(" #n ")" ::: "memory")
; #define BAR __builtin_amdgcn_s_barrier()
; #define SCHED __builtin_amdgcn_sched_barrier(0)
; template <int MODE>
; __device__ __forceinline__ void gemm_tile(const int ph, const int which, const int pm, const int pn) {
;     ...
;     BAR; WAIT_L(0); MMA(1, 0, At, B0); BAR; SCHED;
;     STAGE(SB(1, 1), RB, bcolB, t + 3);
;     WAIT_V(6); BAR; MMA(1, 1, At, B1); BAR;
;   }
;   {
;     LDB(B0, 0, 0); LDA(At, 0, 0); STAGE(SA(1, 1), RA, brow + HALF, nt - 1);
;     BAR; WAIT_L(0); MMA(0, 0, At, B0); BAR;
;     LDB(B1, 0, 1); BAR; WAIT_L(0); MMA(0, 1, At, B1); BAR;
	s_waitcnt lgkmcnt(0)
	s_setprio 1
	s_waitcnt lgkmcnt(7)
	v_mfma_f32_16x16x32_bf16 v[14:17], v[156:159], v[180:183], v[14:17]
	v_mfma_f32_16x16x32_bf16 v[26:29], v[172:175], v[180:183], v[26:29]
	s_waitcnt lgkmcnt(5)
	v_mfma_f32_16x16x32_bf16 v[38:41], v[156:159], v[188:191], v[38:41]
	v_mfma_f32_16x16x32_bf16 v[50:53], v[172:175], v[188:191], v[50:53]
	s_waitcnt lgkmcnt(3)
	v_mfma_f32_16x16x32_bf16 v[62:65], v[156:159], v[196:199], v[62:65]
	v_mfma_f32_16x16x32_bf16 v[74:77], v[172:175], v[196:199], v[74:77]
	s_waitcnt lgkmcnt(1)
	v_mfma_f32_16x16x32_bf16 v[86:89], v[156:159], v[204:207], v[86:89]
	v_mfma_f32_16x16x32_bf16 v[98:101], v[172:175], v[204:207], v[98:101]
	v_mfma_f32_16x16x32_bf16 v[14:17], v[168:171], v[184:187], v[14:17]
	v_mfma_f32_16x16x32_bf16 v[26:29], v[176:179], v[184:187], v[26:29]
	v_mfma_f32_16x16x32_bf16 v[38:41], v[168:171], v[192:195], v[38:41]
	v_mfma_f32_16x16x32_bf16 v[50:53], v[176:179], v[192:195], v[50:53]
	v_mfma_f32_16x16x32_bf16 v[62:65], v[168:171], v[200:203], v[62:65]
	v_mfma_f32_16x16x32_bf16 v[74:77], v[176:179], v[200:203], v[74:77]
	s_waitcnt lgkmcnt(0)
	v_mfma_f32_16x16x32_bf16 v[86:89], v[168:171], v[210:213], v[86:89]
	v_mfma_f32_16x16x32_bf16 v[98:101], v[176:179], v[210:213], v[98:101]
	s_setprio 0
	s_barrier
	v_readfirstlane_b32 s12, v150
	s_addk_i32 s38, 0x180
	s_mov_b32 m0, s12
	v_readfirstlane_b32 s12, v152
	buffer_load_dwordx4 v130, s[68:71], s38 offen lds
	s_addk_i32 s43, 0x180
	s_mov_b32 m0, s12
	s_nop 0
	buffer_load_dwordx4 v130, s[68:71], s43 offen lds
	s_waitcnt vmcnt(6)
	s_barrier
	s_setprio 1
	v_mfma_f32_16x16x32_bf16 v[90:93], v[236:239], v[180:183], v[90:93]
	v_mfma_f32_16x16x32_bf16 v[102:105], v[244:247], v[180:183], v[102:105]
	v_mfma_f32_16x16x32_bf16 v[106:109], v[236:239], v[188:191], v[106:109]
	v_mfma_f32_16x16x32_bf16 v[110:113], v[244:247], v[188:191], v[110:113]
	v_mfma_f32_16x16x32_bf16 v[114:117], v[236:239], v[196:199], v[114:117]
	v_mfma_f32_16x16x32_bf16 v[118:121], v[244:247], v[196:199], v[118:121]
	v_mfma_f32_16x16x32_bf16 v[122:125], v[236:239], v[204:207], v[122:125]
	v_mfma_f32_16x16x32_bf16 v[126:129], v[244:247], v[204:207], v[126:129]
	v_mfma_f32_16x16x32_bf16 v[90:93], v[240:243], v[184:187], v[90:93]
	v_mfma_f32_16x16x32_bf16 v[102:105], v[248:251], v[184:187], v[102:105]
	v_mfma_f32_16x16x32_bf16 v[106:109], v[240:243], v[192:195], v[106:109]
	v_mfma_f32_16x16x32_bf16 v[110:113], v[248:251], v[192:195], v[110:113]
	v_mfma_f32_16x16x32_bf16 v[114:117], v[240:243], v[200:203], v[114:117]
	v_mfma_f32_16x16x32_bf16 v[118:121], v[248:251], v[200:203], v[118:121]
	v_mfma_f32_16x16x32_bf16 v[122:125], v[240:243], v[210:213], v[122:125]
	v_mfma_f32_16x16x32_bf16 v[126:129], v[248:251], v[210:213], v[126:129]
	s_setprio 0
	s_addk_i32 s21, 0x100
	s_cmp_lt_u32 s22, s2
	s_cbranch_scc1 .Lgemm_head_370
	s_barrier
	s_add_i32 s2, s26, s9
	s_lshl_b32 s2, s2, 1
	v_readfirstlane_b32 s3, v151
	s_addk_i32 s2, 0xff80
	s_mov_b32 s6, s70
	s_mov_b32 s7, s71
	s_mov_b32 m0, s3
	v_readfirstlane_b32 s3, v149
	ds_read_b128 v[132:135], v154
	ds_read_b128 v[144:147], v154 offset:1024
	ds_read_b128 v[156:159], v154 offset:2048
	ds_read_b128 v[168:171], v154 offset:3072
	ds_read_b128 v[172:175], v141
	ds_read_b128 v[176:179], v141 offset:1024
	ds_read_b128 v[180:183], v140
	ds_read_b128 v[184:187], v140 offset:1024
	ds_read_b128 v[188:191], v139
	ds_read_b128 v[192:195], v139 offset:1024
	ds_read_b128 v[196:199], v138
	ds_read_b128 v[200:203], v138 offset:1024
	buffer_load_dwordx4 v130, s[4:7], s2 offen lds
	s_add_i32 s2, s2, s8
	s_mov_b32 m0, s3
	s_nop 0
	buffer_load_dwordx4 v130, s[4:7], s2 offen lds
	s_barrier
	s_waitcnt lgkmcnt(0)
	s_setprio 1
	s_waitcnt lgkmcnt(7)
	v_mfma_f32_16x16x32_bf16 v[2:5], v[132:135], v[172:175], v[2:5]
	v_mfma_f32_16x16x32_bf16 v[6:9], v[156:159], v[172:175], v[6:9]
	s_waitcnt lgkmcnt(5)
	v_mfma_f32_16x16x32_bf16 v[18:21], v[132:135], v[180:183], v[18:21]
	s_waitcnt lgkmcnt(1)
	v_mfma_f32_16x16x32_bf16 v[66:69], v[132:135], v[196:199], v[66:69]
	v_mfma_f32_16x16x32_bf16 v[78:81], v[156:159], v[196:199], v[78:81]
	v_mfma_f32_16x16x32_bf16 v[2:5], v[144:147], v[176:179], v[2:5]
	v_mfma_f32_16x16x32_bf16 v[6:9], v[168:171], v[176:179], v[6:9]
	v_mfma_f32_16x16x32_bf16 v[18:21], v[144:147], v[184:187], v[18:21]
	v_mfma_f32_16x16x32_bf16 v[30:33], v[156:159], v[180:183], v[30:33]
	v_mfma_f32_16x16x32_bf16 v[42:45], v[132:135], v[188:191], v[42:45]
	v_mfma_f32_16x16x32_bf16 v[54:57], v[156:159], v[188:191], v[54:57]
	s_waitcnt lgkmcnt(0)
	v_mfma_f32_16x16x32_bf16 v[66:69], v[144:147], v[200:203], v[66:69]
	v_mfma_f32_16x16x32_bf16 v[78:81], v[168:171], v[200:203], v[78:81]
	v_mfma_f32_16x16x32_bf16 v[30:33], v[168:171], v[184:187], v[30:33]
	v_mfma_f32_16x16x32_bf16 v[42:45], v[144:147], v[192:195], v[42:45]
	v_mfma_f32_16x16x32_bf16 v[54:57], v[168:171], v[192:195], v[54:57]
	s_setprio 0
	s_barrier
	ds_read_b128 v[148:151], v153
	ds_read_b128 v[204:207], v153 offset:1024
	ds_read_b128 v[210:213], v153 offset:2048
	ds_read_b128 v[152:155], v153 offset:3072
	s_barrier
; #define WAIT_V(n) asm volatile("s_waitcnt vmcnt(" #n ")" ::: "memory")
; #define WAIT_L(n) asm volatile("s_waitcnt lgkmcnt(" #n ")" ::: "memory")
; #define BAR __builtin_amdgcn_s_barrier()
; template <int MODE>
; __device__ __forceinline__ void gemm_tile(const int ph, const int which, const int pm, const int pn) {
;     ...
;     LDB(B1, 0, 1); BAR; WAIT_L(0); MMA(0, 1, At, B1); BAR;
;     LDA(At, 0, 1); WAIT_V(4); BAR; WAIT_L(0); MMA(1, 0, At, B0); MMA(1, 1, At, B1); BAR;
;   }
;   {
;     LDB(B0, 1, 0); LDA(At, 1, 0); WAIT_V(2); BAR; WAIT_L(0); MMA(0, 0, At, B0); BAR;
	s_waitcnt lgkmcnt(0)
	s_setprio 1
	s_waitcnt lgkmcnt(3)
	v_mfma_f32_16x16x32_bf16 v[10:13], v[148:151], v[172:175], v[10:13]
	s_waitcnt lgkmcnt(1)
	v_mfma_f32_16x16x32_bf16 v[22:25], v[210:213], v[172:175], v[22:25]
	v_mfma_f32_16x16x32_bf16 v[58:61], v[148:151], v[188:191], v[58:61]
	v_mfma_f32_16x16x32_bf16 v[70:73], v[210:213], v[188:191], v[70:73]
	v_mfma_f32_16x16x32_bf16 v[82:85], v[148:151], v[196:199], v[82:85]
	v_mfma_f32_16x16x32_bf16 v[10:13], v[204:207], v[176:179], v[10:13]
	s_waitcnt lgkmcnt(0)
	v_mfma_f32_16x16x32_bf16 v[22:25], v[152:155], v[176:179], v[22:25]
	v_mfma_f32_16x16x32_bf16 v[34:37], v[148:151], v[180:183], v[34:37]
	v_mfma_f32_16x16x32_bf16 v[46:49], v[210:213], v[180:183], v[46:49]
	v_mfma_f32_16x16x32_bf16 v[58:61], v[204:207], v[192:195], v[58:61]
	v_mfma_f32_16x16x32_bf16 v[70:73], v[152:155], v[192:195], v[70:73]
	v_mfma_f32_16x16x32_bf16 v[172:175], v[204:207], v[200:203], v[82:85]
	v_mfma_f32_16x16x32_bf16 v[82:85], v[210:213], v[196:199], v[94:97]
	v_mfma_f32_16x16x32_bf16 v[34:37], v[204:207], v[184:187], v[34:37]
	v_mfma_f32_16x16x32_bf16 v[46:49], v[152:155], v[184:187], v[46:49]
	v_mfma_f32_16x16x32_bf16 v[176:179], v[152:155], v[200:203], v[82:85]
	s_setprio 0
	s_barrier
	s_nop 2
	ds_read_b128 v[82:85], v141 offset:16384
	ds_read_b128 v[94:97], v141 offset:17408
	ds_read_b128 v[180:183], v140 offset:16384
	ds_read_b128 v[184:187], v140 offset:17408
	ds_read_b128 v[188:191], v139 offset:16384
	ds_read_b128 v[192:195], v139 offset:17408
	ds_read_b128 v[196:199], v138 offset:16384
	ds_read_b128 v[200:203], v138 offset:17408
	s_waitcnt vmcnt(4)
	s_barrier
	s_waitcnt lgkmcnt(0)
	s_setprio 1
	s_waitcnt lgkmcnt(3)
	v_mfma_f32_16x16x32_bf16 v[74:77], v[156:159], v[188:191], v[74:77]
	s_waitcnt lgkmcnt(2)
	v_mfma_f32_16x16x32_bf16 v[236:239], v[168:171], v[192:195], v[74:77]
	s_waitcnt lgkmcnt(1)
	v_mfma_f32_16x16x32_bf16 v[74:77], v[132:135], v[196:199], v[86:89]
	v_mfma_f32_16x16x32_bf16 v[14:17], v[132:135], v[82:85], v[14:17]
	v_mfma_f32_16x16x32_bf16 v[62:65], v[132:135], v[188:191], v[62:65]
	s_waitcnt lgkmcnt(0)
	v_mfma_f32_16x16x32_bf16 v[240:243], v[144:147], v[200:203], v[74:77]
	v_mfma_f32_16x16x32_bf16 v[74:77], v[156:159], v[196:199], v[98:101]
	v_mfma_f32_16x16x32_bf16 v[14:17], v[144:147], v[94:97], v[14:17]
	v_mfma_f32_16x16x32_bf16 v[26:29], v[156:159], v[82:85], v[26:29]
	v_mfma_f32_16x16x32_bf16 v[38:41], v[132:135], v[180:183], v[38:41]
	v_mfma_f32_16x16x32_bf16 v[50:53], v[156:159], v[180:183], v[50:53]
	v_mfma_f32_16x16x32_bf16 v[62:65], v[144:147], v[192:195], v[62:65]
	v_mfma_f32_16x16x32_bf16 v[98:101], v[168:171], v[200:203], v[74:77]
	v_mfma_f32_16x16x32_bf16 v[26:29], v[168:171], v[94:97], v[26:29]
	v_mfma_f32_16x16x32_bf16 v[38:41], v[144:147], v[184:187], v[38:41]
	v_mfma_f32_16x16x32_bf16 v[50:53], v[168:171], v[184:187], v[50:53]
	s_setprio 0
	s_setprio 1
	v_mfma_f32_16x16x32_bf16 v[74:77], v[148:151], v[82:85], v[90:93]
	v_mfma_f32_16x16x32_bf16 v[168:171], v[204:207], v[94:97], v[74:77]
	v_mfma_f32_16x16x32_bf16 v[74:77], v[210:213], v[82:85], v[102:105]
	v_mfma_f32_16x16x32_bf16 v[244:247], v[152:155], v[94:97], v[74:77]
	v_mfma_f32_16x16x32_bf16 v[74:77], v[148:151], v[180:183], v[106:109]
	v_mfma_f32_16x16x32_bf16 v[248:251], v[204:207], v[184:187], v[74:77]
	v_mfma_f32_16x16x32_bf16 v[74:77], v[210:213], v[180:183], v[110:113]
	v_mfma_f32_16x16x32_bf16 v[180:183], v[152:155], v[184:187], v[74:77]
	v_mfma_f32_16x16x32_bf16 v[74:77], v[148:151], v[188:191], v[114:117]
	v_mfma_f32_16x16x32_bf16 v[184:187], v[204:207], v[192:195], v[74:77]
	v_mfma_f32_16x16x32_bf16 v[74:77], v[210:213], v[188:191], v[118:121]
	v_mfma_f32_16x16x32_bf16 v[188:191], v[152:155], v[192:195], v[74:77]
	v_mfma_f32_16x16x32_bf16 v[74:77], v[148:151], v[196:199], v[122:125]
	v_mfma_f32_16x16x32_bf16 v[192:195], v[204:207], v[200:203], v[74:77]
	v_mfma_f32_16x16x32_bf16 v[74:77], v[210:213], v[196:199], v[126:129]
	v_mfma_f32_16x16x32_bf16 v[196:199], v[152:155], v[200:203], v[74:77]
	s_setprio 0
	s_barrier
	ds_read_b128 v[102:105], v137
	ds_read_b128 v[200:203], v137 offset:1024
	ds_read_b128 v[204:207], v137 offset:2048
	ds_read_b128 v[210:213], v137 offset:3072
	s_nop 0
	ds_read_b128 v[74:77], v141 offset:32768
	ds_read_b128 v[82:85], v141 offset:33792
	ds_read_b128 v[144:147], v140 offset:32768
	ds_read_b128 v[148:151], v140 offset:33792
	ds_read_b128 v[152:155], v139 offset:32768
	ds_read_b128 v[156:159], v139 offset:33792
	ds_read_b128 v[218:221], v138 offset:32768
	ds_read_b128 v[230:233], v138 offset:33792
	s_waitcnt vmcnt(2)
	s_barrier
	s_waitcnt lgkmcnt(0)
	s_setprio 1
	s_waitcnt lgkmcnt(7)
	v_mfma_f32_16x16x32_bf16 v[2:5], v[102:105], v[74:77], v[2:5]
	s_waitcnt lgkmcnt(6)
	v_mfma_f32_16x16x32_bf16 v[106:109], v[200:203], v[82:85], v[2:5]
	v_mfma_f32_16x16x32_bf16 v[2:5], v[204:207], v[74:77], v[6:9]
	v_mfma_f32_16x16x32_bf16 v[110:113], v[210:213], v[82:85], v[2:5]
	s_waitcnt lgkmcnt(5)
	v_mfma_f32_16x16x32_bf16 v[2:5], v[102:105], v[144:147], v[18:21]
	s_waitcnt lgkmcnt(4)
	v_mfma_f32_16x16x32_bf16 v[114:117], v[200:203], v[148:151], v[2:5]
	v_mfma_f32_16x16x32_bf16 v[2:5], v[204:207], v[144:147], v[30:33]
	v_mfma_f32_16x16x32_bf16 v[118:121], v[210:213], v[148:151], v[2:5]
	s_waitcnt lgkmcnt(3)
	v_mfma_f32_16x16x32_bf16 v[2:5], v[102:105], v[152:155], v[42:45]
	s_waitcnt lgkmcnt(2)
	v_mfma_f32_16x16x32_bf16 v[122:125], v[200:203], v[156:159], v[2:5]
	v_mfma_f32_16x16x32_bf16 v[2:5], v[204:207], v[152:155], v[54:57]
	v_mfma_f32_16x16x32_bf16 v[126:129], v[210:213], v[156:159], v[2:5]
	s_waitcnt lgkmcnt(1)
	v_mfma_f32_16x16x32_bf16 v[2:5], v[102:105], v[218:221], v[66:69]
	s_waitcnt lgkmcnt(0)
	v_mfma_f32_16x16x32_bf16 v[130:133], v[200:203], v[230:233], v[2:5]
	v_mfma_f32_16x16x32_bf16 v[2:5], v[204:207], v[218:221], v[78:81]
	v_mfma_f32_16x16x32_bf16 v[134:137], v[210:213], v[230:233], v[2:5]
	s_setprio 0
	s_barrier
; #define WAIT_V(n) asm volatile("s_waitcnt vmcnt(" #n ")" ::: "memory")
; #define WAIT_L(n) asm volatile("s_waitcnt lgkmcnt(" #n ")" ::: "memory")
; #define BAR __builtin_amdgcn_s_barrier()
; template <int MODE>
; __device__ __forceinline__ void gemm_tile(const int ph, const int which, const int pm, const int pn) {
;     ...
;     LDB(B0, 1, 0); LDA(At, 1, 0); WAIT_V(2); BAR; WAIT_L(0); MMA(0, 0, At, B0); BAR;
;     LDB(B1, 1, 1); WAIT_V(0); BAR; WAIT_L(0); MMA(0, 1, At, B1); BAR;
;     LDA(At, 1, 1); BAR; WAIT_L(0); MMA(1, 0, At, B0); MMA(1, 1, At, B1); BAR;
;   }
;   if (wr == 0) BAR;
;   bf16_t* C; bf16_t* C2; const float* scale; const float* cw; const float* cb; int ldc, act, browC, ecol;
;   {
;     int ph2 = ph;
;     asm volatile("" : "+s"(ph2));
;     const Params p = load_params();
;     const GD g = make_gd(p, ph2, which);
;     TileP tp; TileE te;
;     tile_setup(g, pm, pn, tp, te);
;     C = te.C; C2 = te.C2; scale = te.scale; cw = te.cw; cb = te.cb; ldc = te.ldc; act = te.act; browC = te.browC; ecol = te.bcol;
;   }
	s_nop 4
	ds_read_b128 v[2:5], v142
	ds_read_b128 v[6:9], v142 offset:1024
	ds_read_b128 v[30:33], v142 offset:2048
	ds_read_b128 v[42:45], v142 offset:3072
	s_waitcnt vmcnt(0)
	s_barrier
	s_waitcnt lgkmcnt(0)
	s_setprio 1
	s_waitcnt lgkmcnt(3)
	v_mfma_f32_16x16x32_bf16 v[10:13], v[2:5], v[74:77], v[10:13]
	s_waitcnt lgkmcnt(2)
	v_mfma_f32_16x16x32_bf16 v[94:97], v[6:9], v[82:85], v[10:13]
	s_waitcnt lgkmcnt(1)
	v_mfma_f32_16x16x32_bf16 v[10:13], v[30:33], v[74:77], v[22:25]
	s_waitcnt lgkmcnt(0)
	v_mfma_f32_16x16x32_bf16 v[90:93], v[42:45], v[82:85], v[10:13]
	v_mfma_f32_16x16x32_bf16 v[10:13], v[2:5], v[144:147], v[34:37]
	v_mfma_f32_16x16x32_bf16 v[86:89], v[6:9], v[148:151], v[10:13]
	v_mfma_f32_16x16x32_bf16 v[10:13], v[30:33], v[144:147], v[46:49]
	v_mfma_f32_16x16x32_bf16 v[82:85], v[42:45], v[148:151], v[10:13]
	v_mfma_f32_16x16x32_bf16 v[10:13], v[2:5], v[152:155], v[58:61]
	v_mfma_f32_16x16x32_bf16 v[78:81], v[6:9], v[156:159], v[10:13]
	v_mfma_f32_16x16x32_bf16 v[10:13], v[30:33], v[152:155], v[70:73]
	v_mfma_f32_16x16x32_bf16 v[74:77], v[42:45], v[156:159], v[10:13]
	v_mfma_f32_16x16x32_bf16 v[10:13], v[2:5], v[218:221], v[172:175]
	v_mfma_f32_16x16x32_bf16 v[70:73], v[6:9], v[230:233], v[10:13]
	v_mfma_f32_16x16x32_bf16 v[10:13], v[30:33], v[218:221], v[176:179]
	v_mfma_f32_16x16x32_bf16 v[66:69], v[42:45], v[230:233], v[10:13]
	s_setprio 0
	s_barrier
	s_nop 4
	ds_read_b128 v[10:13], v141 offset:49152
	ds_read_b128 v[18:21], v141 offset:50176
	ds_read_b128 v[34:37], v140 offset:49152
	ds_read_b128 v[46:49], v140 offset:50176
	ds_read_b128 v[54:57], v139 offset:49152
	ds_read_b128 v[172:175], v139 offset:50176
	ds_read_b128 v[176:179], v138 offset:49152
	ds_read_b128 v[218:221], v138 offset:50176
	s_barrier
	s_waitcnt lgkmcnt(0)
	s_setprio 1
	s_waitcnt lgkmcnt(7)
	v_mfma_f32_16x16x32_bf16 v[14:17], v[102:105], v[10:13], v[14:17]
	s_waitcnt lgkmcnt(6)
	v_mfma_f32_16x16x32_bf16 v[158:161], v[200:203], v[18:21], v[14:17]
	v_mfma_f32_16x16x32_bf16 v[14:17], v[204:207], v[10:13], v[26:29]
	v_mfma_f32_16x16x32_bf16 v[154:157], v[210:213], v[18:21], v[14:17]
	s_waitcnt lgkmcnt(5)
	v_mfma_f32_16x16x32_bf16 v[14:17], v[102:105], v[34:37], v[38:41]
	s_waitcnt lgkmcnt(4)
	v_mfma_f32_16x16x32_bf16 v[150:153], v[200:203], v[46:49], v[14:17]
	v_mfma_f32_16x16x32_bf16 v[14:17], v[204:207], v[34:37], v[50:53]
	v_mfma_f32_16x16x32_bf16 v[146:149], v[210:213], v[46:49], v[14:17]
	s_waitcnt lgkmcnt(3)
	v_mfma_f32_16x16x32_bf16 v[14:17], v[102:105], v[54:57], v[62:65]
	s_waitcnt lgkmcnt(2)
	v_mfma_f32_16x16x32_bf16 v[142:145], v[200:203], v[172:175], v[14:17]
	v_mfma_f32_16x16x32_bf16 v[14:17], v[204:207], v[54:57], v[236:239]
	v_mfma_f32_16x16x32_bf16 v[138:141], v[210:213], v[172:175], v[14:17]
	s_waitcnt lgkmcnt(1)
	v_mfma_f32_16x16x32_bf16 v[14:17], v[102:105], v[176:179], v[240:243]
	s_waitcnt lgkmcnt(0)
	v_mfma_f32_16x16x32_bf16 v[102:105], v[200:203], v[218:221], v[14:17]
	v_mfma_f32_16x16x32_bf16 v[14:17], v[204:207], v[176:179], v[98:101]
	v_mfma_f32_16x16x32_bf16 v[98:101], v[210:213], v[218:221], v[14:17]
	s_setprio 0
	s_setprio 1
	v_mfma_f32_16x16x32_bf16 v[14:17], v[2:5], v[10:13], v[168:171]
	v_mfma_f32_16x16x32_bf16 v[10:13], v[30:33], v[10:13], v[244:247]
	v_mfma_f32_16x16x32_bf16 v[58:61], v[42:45], v[18:21], v[10:13]
	v_mfma_f32_16x16x32_bf16 v[10:13], v[2:5], v[34:37], v[248:251]
	v_mfma_f32_16x16x32_bf16 v[22:25], v[6:9], v[46:49], v[10:13]
	v_mfma_f32_16x16x32_bf16 v[10:13], v[30:33], v[34:37], v[180:183]
	v_mfma_f32_16x16x32_bf16 v[62:65], v[6:9], v[18:21], v[14:17]
	v_mfma_f32_16x16x32_bf16 v[18:21], v[42:45], v[46:49], v[10:13]
	v_mfma_f32_16x16x32_bf16 v[10:13], v[2:5], v[54:57], v[184:187]
	v_mfma_f32_16x16x32_bf16 v[2:5], v[2:5], v[176:179], v[192:195]
	v_mfma_f32_16x16x32_bf16 v[14:17], v[6:9], v[172:175], v[10:13]
	v_mfma_f32_16x16x32_bf16 v[10:13], v[30:33], v[54:57], v[188:191]
	v_mfma_f32_16x16x32_bf16 v[6:9], v[6:9], v[218:221], v[2:5]
	v_mfma_f32_16x16x32_bf16 v[2:5], v[30:33], v[176:179], v[196:199]
	v_mfma_f32_16x16x32_bf16 v[10:13], v[42:45], v[172:175], v[10:13]
	v_mfma_f32_16x16x32_bf16 v[2:5], v[42:45], v[218:221], v[2:5]
	s_setprio 0
	s_load_dwordx4 s[4:7], s[0:1], 0xf0
	s_load_dwordx4 s[8:11], s[0:1], 0xd8
	s_movk_i32 s2, 0x100
	v_cmp_gt_u32_e32 vcc, s2, v164
	s_barrier
	s_and_saveexec_b64 s[2:3], vcc
	s_cbranch_execz .LBB0_373
	s_barrier
.LBB0_373:
	s_or_b64 exec, exec, s[2:3]
	s_mov_b32 s28, s34
	s_mov_b64 s[2:3], s[0:1]
	s_mov_b64 s[18:19], -1
	s_mov_b64 s[22:23], 0
	s_mov_b64 s[2:3], 0
	s_waitcnt lgkmcnt(0)
	s_add_u32 s16, s6, 0x3be6000
	s_addc_u32 s17, s7, 0
	s_add_u32 s26, s6, 0xe1a6000
	s_addc_u32 s27, s7, 0
	s_cmp_lt_i32 s28, 3
	s_cbranch_scc1 .LBB0_382
	s_cmp_gt_i32 s28, 16
	s_cbranch_scc0 .LBB0_376
	s_cmp_lg_u32 s28, 17
	s_mov_b64 s[18:19], 0
	s_cselect_b64 s[2:3], -1, 0

; #define WAIT_V(n) asm volatile("s_waitcnt vmcnt(" #n ")" ::: "memory")
; #define WAIT_L(n) asm volatile("s_waitcnt lgkmcnt(" #n ")" ::: "memory")
; #define BAR __builtin_amdgcn_s_barrier()
; #define SCHED __builtin_amdgcn_sched_barrier(0)
; template <int MODE>
; __device__ __forceinline__ void gemm_tile(const int ph, const int which, const int pm, const int pn) {
;     ...
;   for (int t = 0; t < nt - 2; t += 2) {
;     LDB(B0, 0, 0); SCHED; LDA(At, 0, 0); STAGE(SA(1, 1), RA, brow + HALF, t + 1);
;     WAIT_L(8); BAR; WAIT_L(0); MMA(0, 0, At, B0); BAR; SCHED;
;     LDB(B1, 0, 1); STAGE(SB(0, 0), RB, bcol, t + 2);
;     BAR; WAIT_L(0); MMA(0, 1, At, B1); BAR;
;     LDA(At, 0, 1); STAGE(SA(0, 0), RA, brow, t + 2);
;     BAR; WAIT_L(0); MMA(1, 0, At, B0); BAR; SCHED;
;     STAGE(SB(0, 1), RB, bcolB, t + 2);
;     WAIT_V(6); BAR; MMA(1, 1, At, B1); BAR;
.LBB0_540:
	ds_read_b128 v[158:161], v156
	ds_read_b128 v[162:165], v156 offset:1024
	ds_read_b128 v[166:169], v156 offset:2048
	ds_read_b128 v[170:173], v156 offset:3072
	s_add_i32 s26, s10, s23
	v_readfirstlane_b32 s28, v153
	s_add_i32 s27, s26, 0x80
	s_mov_b32 m0, s28
	ds_read_b128 v[174:177], v135
	ds_read_b128 v[178:181], v135 offset:1024
	ds_read_b128 v[182:185], v134
	ds_read_b128 v[186:189], v134 offset:1024
	ds_read_b128 v[190:193], v133
	ds_read_b128 v[194:197], v133 offset:1024
	ds_read_b128 v[198:201], v132
	ds_read_b128 v[202:205], v132 offset:1024
	buffer_load_dwordx4 v136, s[4:7], s27 offen lds
	s_add_i32 s27, s3, s23
	v_readfirstlane_b32 s51, v151
	s_add_i32 s28, s27, 0x80
	s_mov_b32 m0, s51
	s_nop 0
	buffer_load_dwordx4 v136, s[4:7], s28 offen lds
	s_waitcnt lgkmcnt(8)
	s_barrier
	s_waitcnt lgkmcnt(0)
	s_setprio 1
	s_waitcnt lgkmcnt(7)
	v_mfma_f32_16x16x32_bf16 v[126:129], v[158:161], v[174:177], v[126:129]
	v_mfma_f32_16x16x32_bf16 v[122:125], v[166:169], v[174:177], v[122:125]
	s_waitcnt lgkmcnt(5)
	v_mfma_f32_16x16x32_bf16 v[118:121], v[158:161], v[182:185], v[118:121]
	v_mfma_f32_16x16x32_bf16 v[114:117], v[166:169], v[182:185], v[114:117]
	s_waitcnt lgkmcnt(3)
	v_mfma_f32_16x16x32_bf16 v[110:113], v[158:161], v[190:193], v[110:113]
	v_mfma_f32_16x16x32_bf16 v[106:109], v[166:169], v[190:193], v[106:109]
	s_waitcnt lgkmcnt(1)
	v_mfma_f32_16x16x32_bf16 v[102:105], v[158:161], v[198:201], v[102:105]
	v_mfma_f32_16x16x32_bf16 v[98:101], v[166:169], v[198:201], v[98:101]
	v_mfma_f32_16x16x32_bf16 v[126:129], v[162:165], v[178:181], v[126:129]
	v_mfma_f32_16x16x32_bf16 v[122:125], v[170:173], v[178:181], v[122:125]
	v_mfma_f32_16x16x32_bf16 v[118:121], v[162:165], v[186:189], v[118:121]
	v_mfma_f32_16x16x32_bf16 v[114:117], v[170:173], v[186:189], v[114:117]
	v_mfma_f32_16x16x32_bf16 v[110:113], v[162:165], v[194:197], v[110:113]
	v_mfma_f32_16x16x32_bf16 v[106:109], v[170:173], v[194:197], v[106:109]
	s_waitcnt lgkmcnt(0)
	v_mfma_f32_16x16x32_bf16 v[102:105], v[162:165], v[202:205], v[102:105]
	v_mfma_f32_16x16x32_bf16 v[98:101], v[170:173], v[202:205], v[98:101]
	s_setprio 0
	s_barrier
	s_add_i32 s28, s22, s23
	v_readfirstlane_b32 s84, v139
	s_add_i32 s51, s28, 0x100
	s_mov_b32 m0, s84
	ds_read_b128 v[236:239], v155
	ds_read_b128 v[240:243], v155 offset:1024
	ds_read_b128 v[244:247], v155 offset:2048
	ds_read_b128 v[248:251], v155 offset:3072
	buffer_load_dwordx4 v136, s[68:71], s51 offen lds
	s_add_i32 s51, s21, s23
	v_readfirstlane_b32 s50, v140
	s_add_i32 s84, s51, 0x100
	s_mov_b32 m0, s50
	s_add_i32 s25, s25, 2
	buffer_load_dwordx4 v136, s[68:71], s84 offen lds
	s_barrier
	s_waitcnt lgkmcnt(0)
	s_setprio 1
	s_waitcnt lgkmcnt(3)
	v_mfma_f32_16x16x32_bf16 v[94:97], v[236:239], v[174:177], v[94:97]
	s_waitcnt lgkmcnt(1)
	v_mfma_f32_16x16x32_bf16 v[90:93], v[244:247], v[174:177], v[90:93]
	v_mfma_f32_16x16x32_bf16 v[86:89], v[236:239], v[182:185], v[86:89]
	v_mfma_f32_16x16x32_bf16 v[82:85], v[244:247], v[182:185], v[82:85]
	v_mfma_f32_16x16x32_bf16 v[78:81], v[236:239], v[190:193], v[78:81]
	v_mfma_f32_16x16x32_bf16 v[74:77], v[244:247], v[190:193], v[74:77]
	v_mfma_f32_16x16x32_bf16 v[70:73], v[236:239], v[198:201], v[70:73]
	v_mfma_f32_16x16x32_bf16 v[66:69], v[244:247], v[198:201], v[66:69]
	v_mfma_f32_16x16x32_bf16 v[94:97], v[240:243], v[178:181], v[94:97]
	s_waitcnt lgkmcnt(0)
	v_mfma_f32_16x16x32_bf16 v[90:93], v[248:251], v[178:181], v[90:93]
	v_mfma_f32_16x16x32_bf16 v[86:89], v[240:243], v[186:189], v[86:89]
	v_mfma_f32_16x16x32_bf16 v[82:85], v[248:251], v[186:189], v[82:85]
	v_mfma_f32_16x16x32_bf16 v[78:81], v[240:243], v[194:197], v[78:81]
	v_mfma_f32_16x16x32_bf16 v[74:77], v[248:251], v[194:197], v[74:77]
	v_mfma_f32_16x16x32_bf16 v[70:73], v[240:243], v[202:205], v[70:73]
	v_mfma_f32_16x16x32_bf16 v[66:69], v[248:251], v[202:205], v[66:69]
	s_setprio 0
	s_add_i32 s50, s20, s23
	v_readfirstlane_b32 s29, v137
	s_add_i32 s84, s50, 0x100
	s_mov_b32 m0, s29
	s_add_i32 s29, s19, s23
	v_readfirstlane_b32 s43, v141
	s_barrier
	ds_read_b128 v[174:177], v135 offset:16384
	ds_read_b128 v[178:181], v135 offset:17408
	ds_read_b128 v[182:185], v134 offset:16384
	ds_read_b128 v[186:189], v134 offset:17408
	ds_read_b128 v[190:193], v133 offset:16384
	ds_read_b128 v[194:197], v133 offset:17408
	ds_read_b128 v[198:201], v132 offset:16384
	ds_read_b128 v[202:205], v132 offset:17408
	buffer_load_dwordx4 v136, s[4:7], s84 offen lds
	s_add_i32 s84, s29, 0x100
	s_mov_b32 m0, s43
	s_nop 0
	buffer_load_dwordx4 v136, s[4:7], s84 offen lds
	s_barrier
	s_waitcnt lgkmcnt(0)
	s_setprio 1
	s_waitcnt lgkmcnt(7)
	v_mfma_f32_16x16x32_bf16 v[62:65], v[158:161], v[174:177], v[62:65]
	v_mfma_f32_16x16x32_bf16 v[58:61], v[166:169], v[174:177], v[58:61]
	s_waitcnt lgkmcnt(5)
	v_mfma_f32_16x16x32_bf16 v[54:57], v[158:161], v[182:185], v[54:57]
	v_mfma_f32_16x16x32_bf16 v[50:53], v[166:169], v[182:185], v[50:53]
	s_waitcnt lgkmcnt(3)
	v_mfma_f32_16x16x32_bf16 v[46:49], v[158:161], v[190:193], v[46:49]
	v_mfma_f32_16x16x32_bf16 v[42:45], v[166:169], v[190:193], v[42:45]
	s_waitcnt lgkmcnt(1)
	v_mfma_f32_16x16x32_bf16 v[38:41], v[158:161], v[198:201], v[38:41]
	v_mfma_f32_16x16x32_bf16 v[34:37], v[166:169], v[198:201], v[34:37]
	v_mfma_f32_16x16x32_bf16 v[62:65], v[162:165], v[178:181], v[62:65]
	v_mfma_f32_16x16x32_bf16 v[58:61], v[170:173], v[178:181], v[58:61]
	v_mfma_f32_16x16x32_bf16 v[54:57], v[162:165], v[186:189], v[54:57]
	v_mfma_f32_16x16x32_bf16 v[50:53], v[170:173], v[186:189], v[50:53]
	v_mfma_f32_16x16x32_bf16 v[46:49], v[162:165], v[194:197], v[46:49]
	v_mfma_f32_16x16x32_bf16 v[42:45], v[170:173], v[194:197], v[42:45]
	s_waitcnt lgkmcnt(0)
	v_mfma_f32_16x16x32_bf16 v[38:41], v[162:165], v[202:205], v[38:41]
	v_mfma_f32_16x16x32_bf16 v[34:37], v[170:173], v[202:205], v[34:37]
	s_setprio 0
	s_barrier
; #define WAIT_V(n) asm volatile("s_waitcnt vmcnt(" #n ")" ::: "memory")
; #define WAIT_L(n) asm volatile("s_waitcnt lgkmcnt(" #n ")" ::: "memory")
; #define BAR __builtin_amdgcn_s_barrier()
; #define SCHED __builtin_amdgcn_sched_barrier(0)
; template <int MODE>
; __device__ __forceinline__ void gemm_tile(const int ph, const int which, const int pm, const int pn) {
;     ...
;     WAIT_V(6); BAR; MMA(1, 1, At, B1); BAR;
;     LDB(B0, 1, 0); SCHED; LDA(At, 1, 0); STAGE(SA(0, 1), RA, brow + HALF, t + 2);
;     WAIT_L(8); BAR; WAIT_L(0); MMA(0, 0, At, B0); BAR; SCHED;
;     LDB(B1, 1, 1); STAGE(SB(1, 0), RB, bcol, t + 3);
;     BAR; WAIT_L(0); MMA(0, 1, At, B1); BAR;
;     LDA(At, 1, 1); STAGE(SA(1, 0), RA, brow, t + 3);
;     BAR; WAIT_L(0); MMA(1, 0, At, B0); BAR; SCHED;
	s_add_i32 s43, s17, s23
	v_readfirstlane_b32 s38, v142
	s_add_i32 s84, s43, 0x100
	s_mov_b32 m0, s38
	s_add_i32 s38, s11, s23
	v_readfirstlane_b32 s12, v143
	buffer_load_dwordx4 v136, s[68:71], s84 offen lds
	s_add_i32 s84, s38, 0x100
	s_mov_b32 m0, s12
	s_nop 0
	buffer_load_dwordx4 v136, s[68:71], s84 offen lds
	s_waitcnt vmcnt(6)
	s_barrier
	s_setprio 1
	v_mfma_f32_16x16x32_bf16 v[30:33], v[236:239], v[174:177], v[30:33]
	v_mfma_f32_16x16x32_bf16 v[26:29], v[244:247], v[174:177], v[26:29]
	v_mfma_f32_16x16x32_bf16 v[22:25], v[236:239], v[182:185], v[22:25]
	v_mfma_f32_16x16x32_bf16 v[18:21], v[244:247], v[182:185], v[18:21]
	v_mfma_f32_16x16x32_bf16 v[14:17], v[236:239], v[190:193], v[14:17]
	v_mfma_f32_16x16x32_bf16 v[10:13], v[244:247], v[190:193], v[10:13]
	v_mfma_f32_16x16x32_bf16 v[6:9], v[236:239], v[198:201], v[6:9]
	v_mfma_f32_16x16x32_bf16 v[2:5], v[244:247], v[198:201], v[2:5]
	v_mfma_f32_16x16x32_bf16 v[30:33], v[240:243], v[178:181], v[30:33]
	v_mfma_f32_16x16x32_bf16 v[26:29], v[248:251], v[178:181], v[26:29]
	v_mfma_f32_16x16x32_bf16 v[22:25], v[240:243], v[186:189], v[22:25]
	v_mfma_f32_16x16x32_bf16 v[18:21], v[248:251], v[186:189], v[18:21]
	v_mfma_f32_16x16x32_bf16 v[14:17], v[240:243], v[194:197], v[14:17]
	v_mfma_f32_16x16x32_bf16 v[10:13], v[248:251], v[194:197], v[10:13]
	v_mfma_f32_16x16x32_bf16 v[6:9], v[240:243], v[202:205], v[6:9]
	v_mfma_f32_16x16x32_bf16 v[2:5], v[248:251], v[202:205], v[2:5]
	s_setprio 0
	s_barrier
	ds_read_b128 v[158:161], v144
	ds_read_b128 v[162:165], v144 offset:1024
	ds_read_b128 v[166:169], v144 offset:2048
	ds_read_b128 v[170:173], v144 offset:3072
	v_readfirstlane_b32 s12, v145
	s_addk_i32 s26, 0x100
	s_mov_b32 m0, s12
	v_readfirstlane_b32 s12, v146
	ds_read_b128 v[174:177], v135 offset:32768
	ds_read_b128 v[178:181], v135 offset:33792
	ds_read_b128 v[182:185], v134 offset:32768
	ds_read_b128 v[186:189], v134 offset:33792
	ds_read_b128 v[190:193], v133 offset:32768
	ds_read_b128 v[194:197], v133 offset:33792
	ds_read_b128 v[198:201], v132 offset:32768
	ds_read_b128 v[202:205], v132 offset:33792
	buffer_load_dwordx4 v136, s[4:7], s26 offen lds
	s_addk_i32 s27, 0x100
	s_mov_b32 m0, s12
	s_nop 0
	buffer_load_dwordx4 v136, s[4:7], s27 offen lds
	s_waitcnt lgkmcnt(8)
	s_barrier
	s_waitcnt lgkmcnt(0)
	s_setprio 1
	s_waitcnt lgkmcnt(7)
	v_mfma_f32_16x16x32_bf16 v[126:129], v[158:161], v[174:177], v[126:129]
	v_mfma_f32_16x16x32_bf16 v[122:125], v[166:169], v[174:177], v[122:125]
	s_waitcnt lgkmcnt(5)
	v_mfma_f32_16x16x32_bf16 v[118:121], v[158:161], v[182:185], v[118:121]
	v_mfma_f32_16x16x32_bf16 v[114:117], v[166:169], v[182:185], v[114:117]
	s_waitcnt lgkmcnt(3)
	v_mfma_f32_16x16x32_bf16 v[110:113], v[158:161], v[190:193], v[110:113]
	v_mfma_f32_16x16x32_bf16 v[106:109], v[166:169], v[190:193], v[106:109]
	s_waitcnt lgkmcnt(1)
	v_mfma_f32_16x16x32_bf16 v[102:105], v[158:161], v[198:201], v[102:105]
	v_mfma_f32_16x16x32_bf16 v[98:101], v[166:169], v[198:201], v[98:101]
	v_mfma_f32_16x16x32_bf16 v[126:129], v[162:165], v[178:181], v[126:129]
	v_mfma_f32_16x16x32_bf16 v[122:125], v[170:173], v[178:181], v[122:125]
	v_mfma_f32_16x16x32_bf16 v[118:121], v[162:165], v[186:189], v[118:121]
	v_mfma_f32_16x16x32_bf16 v[114:117], v[170:173], v[186:189], v[114:117]
	v_mfma_f32_16x16x32_bf16 v[110:113], v[162:165], v[194:197], v[110:113]
	v_mfma_f32_16x16x32_bf16 v[106:109], v[170:173], v[194:197], v[106:109]
	s_waitcnt lgkmcnt(0)
	v_mfma_f32_16x16x32_bf16 v[102:105], v[162:165], v[202:205], v[102:105]
	v_mfma_f32_16x16x32_bf16 v[98:101], v[170:173], v[202:205], v[98:101]
	s_setprio 0
	s_barrier
	v_readfirstlane_b32 s12, v147
	s_addk_i32 s28, 0x180
	s_mov_b32 m0, s12
	v_readfirstlane_b32 s12, v148
	ds_read_b128 v[236:239], v138
	ds_read_b128 v[240:243], v138 offset:1024
	ds_read_b128 v[244:247], v138 offset:2048
	ds_read_b128 v[248:251], v138 offset:3072
	buffer_load_dwordx4 v136, s[68:71], s28 offen lds
	s_addk_i32 s51, 0x180
	s_mov_b32 m0, s12
	s_nop 0
	buffer_load_dwordx4 v136, s[68:71], s51 offen lds
	s_barrier
	s_waitcnt lgkmcnt(0)
	s_setprio 1
	s_waitcnt lgkmcnt(3)
	v_mfma_f32_16x16x32_bf16 v[94:97], v[236:239], v[174:177], v[94:97]
	s_waitcnt lgkmcnt(1)
	v_mfma_f32_16x16x32_bf16 v[90:93], v[244:247], v[174:177], v[90:93]
	v_mfma_f32_16x16x32_bf16 v[86:89], v[236:239], v[182:185], v[86:89]
	v_mfma_f32_16x16x32_bf16 v[82:85], v[244:247], v[182:185], v[82:85]
	v_mfma_f32_16x16x32_bf16 v[78:81], v[236:239], v[190:193], v[78:81]
	v_mfma_f32_16x16x32_bf16 v[74:77], v[244:247], v[190:193], v[74:77]
	v_mfma_f32_16x16x32_bf16 v[70:73], v[236:239], v[198:201], v[70:73]
	v_mfma_f32_16x16x32_bf16 v[66:69], v[244:247], v[198:201], v[66:69]
	v_mfma_f32_16x16x32_bf16 v[94:97], v[240:243], v[178:181], v[94:97]
	s_waitcnt lgkmcnt(0)
	v_mfma_f32_16x16x32_bf16 v[90:93], v[248:251], v[178:181], v[90:93]
	v_mfma_f32_16x16x32_bf16 v[86:89], v[240:243], v[186:189], v[86:89]
	v_mfma_f32_16x16x32_bf16 v[82:85], v[248:251], v[186:189], v[82:85]
	v_mfma_f32_16x16x32_bf16 v[78:81], v[240:243], v[194:197], v[78:81]
	v_mfma_f32_16x16x32_bf16 v[74:77], v[248:251], v[194:197], v[74:77]
	v_mfma_f32_16x16x32_bf16 v[70:73], v[240:243], v[202:205], v[70:73]
	v_mfma_f32_16x16x32_bf16 v[66:69], v[248:251], v[202:205], v[66:69]
	s_setprio 0
	v_readfirstlane_b32 s12, v149
	s_addk_i32 s50, 0x180
	s_mov_b32 m0, s12
	v_readfirstlane_b32 s12, v150
	s_barrier
	ds_read_b128 v[174:177], v135 offset:49152
	ds_read_b128 v[178:181], v135 offset:50176
	ds_read_b128 v[182:185], v134 offset:49152
	ds_read_b128 v[186:189], v134 offset:50176
	ds_read_b128 v[190:193], v133 offset:49152
	ds_read_b128 v[194:197], v133 offset:50176
	ds_read_b128 v[198:201], v132 offset:49152
	ds_read_b128 v[202:205], v132 offset:50176
	buffer_load_dwordx4 v136, s[4:7], s50 offen lds
	s_addk_i32 s29, 0x180
	s_mov_b32 m0, s12
	s_nop 0
	buffer_load_dwordx4 v136, s[4:7], s29 offen lds
	s_barrier
; #define WAIT_V(n) asm volatile("s_waitcnt vmcnt(" #n ")" ::: "memory")
; #define WAIT_L(n) asm volatile("s_waitcnt lgkmcnt(" #n ")" ::: "memory")
; #define BAR __builtin_amdgcn_s_barrier()
; #define SCHED __builtin_amdgcn_sched_barrier(0)
; template <int MODE>
; __device__ __forceinline__ void gemm_tile(const int ph, const int which, const int pm, const int pn) {
;     ...
;     BAR; WAIT_L(0); MMA(1, 0, At, B0); BAR; SCHED;
;     STAGE(SB(1, 1), RB, bcolB, t + 3);
;     WAIT_V(6); BAR; MMA(1, 1, At, B1); BAR;
;   }
;   {
;     LDB(B0, 0, 0); LDA(At, 0, 0); STAGE(SA(1, 1), RA, brow + HALF, nt - 1);
;     BAR; WAIT_L(0); MMA(0, 0, At, B0); BAR;
;     LDB(B1, 0, 1); BAR; WAIT_L(0); MMA(0, 1, At, B1); BAR;
	s_waitcnt lgkmcnt(0)
	s_setprio 1
	s_waitcnt lgkmcnt(7)
	v_mfma_f32_16x16x32_bf16 v[62:65], v[158:161], v[174:177], v[62:65]
	v_mfma_f32_16x16x32_bf16 v[58:61], v[166:169], v[174:177], v[58:61]
	s_waitcnt lgkmcnt(5)
	v_mfma_f32_16x16x32_bf16 v[54:57], v[158:161], v[182:185], v[54:57]
	v_mfma_f32_16x16x32_bf16 v[50:53], v[166:169], v[182:185], v[50:53]
	s_waitcnt lgkmcnt(3)
	v_mfma_f32_16x16x32_bf16 v[46:49], v[158:161], v[190:193], v[46:49]
	v_mfma_f32_16x16x32_bf16 v[42:45], v[166:169], v[190:193], v[42:45]
	s_waitcnt lgkmcnt(1)
	v_mfma_f32_16x16x32_bf16 v[38:41], v[158:161], v[198:201], v[38:41]
	v_mfma_f32_16x16x32_bf16 v[34:37], v[166:169], v[198:201], v[34:37]
	v_mfma_f32_16x16x32_bf16 v[62:65], v[162:165], v[178:181], v[62:65]
	v_mfma_f32_16x16x32_bf16 v[58:61], v[170:173], v[178:181], v[58:61]
	v_mfma_f32_16x16x32_bf16 v[54:57], v[162:165], v[186:189], v[54:57]
	v_mfma_f32_16x16x32_bf16 v[50:53], v[170:173], v[186:189], v[50:53]
	v_mfma_f32_16x16x32_bf16 v[46:49], v[162:165], v[194:197], v[46:49]
	v_mfma_f32_16x16x32_bf16 v[42:45], v[170:173], v[194:197], v[42:45]
	s_waitcnt lgkmcnt(0)
	v_mfma_f32_16x16x32_bf16 v[38:41], v[162:165], v[202:205], v[38:41]
	v_mfma_f32_16x16x32_bf16 v[34:37], v[170:173], v[202:205], v[34:37]
	s_setprio 0
	s_barrier
	v_readfirstlane_b32 s12, v152
	s_addk_i32 s43, 0x180
	s_mov_b32 m0, s12
	v_readfirstlane_b32 s12, v154
	buffer_load_dwordx4 v136, s[68:71], s43 offen lds
	s_addk_i32 s38, 0x180
	s_mov_b32 m0, s12
	s_nop 0
	buffer_load_dwordx4 v136, s[68:71], s38 offen lds
	s_waitcnt vmcnt(6)
	s_barrier
	s_setprio 1
	v_mfma_f32_16x16x32_bf16 v[30:33], v[236:239], v[174:177], v[30:33]
	v_mfma_f32_16x16x32_bf16 v[26:29], v[244:247], v[174:177], v[26:29]
	v_mfma_f32_16x16x32_bf16 v[22:25], v[236:239], v[182:185], v[22:25]
	v_mfma_f32_16x16x32_bf16 v[18:21], v[244:247], v[182:185], v[18:21]
	v_mfma_f32_16x16x32_bf16 v[14:17], v[236:239], v[190:193], v[14:17]
	v_mfma_f32_16x16x32_bf16 v[10:13], v[244:247], v[190:193], v[10:13]
	v_mfma_f32_16x16x32_bf16 v[6:9], v[236:239], v[198:201], v[6:9]
	v_mfma_f32_16x16x32_bf16 v[2:5], v[244:247], v[198:201], v[2:5]
	v_mfma_f32_16x16x32_bf16 v[30:33], v[240:243], v[178:181], v[30:33]
	v_mfma_f32_16x16x32_bf16 v[26:29], v[248:251], v[178:181], v[26:29]
	v_mfma_f32_16x16x32_bf16 v[22:25], v[240:243], v[186:189], v[22:25]
	v_mfma_f32_16x16x32_bf16 v[18:21], v[248:251], v[186:189], v[18:21]
	v_mfma_f32_16x16x32_bf16 v[14:17], v[240:243], v[194:197], v[14:17]
	v_mfma_f32_16x16x32_bf16 v[10:13], v[248:251], v[194:197], v[10:13]
	v_mfma_f32_16x16x32_bf16 v[6:9], v[240:243], v[202:205], v[6:9]
	v_mfma_f32_16x16x32_bf16 v[2:5], v[248:251], v[202:205], v[2:5]
	s_setprio 0
	s_addk_i32 s23, 0x100
	s_cmp_lt_u32 s25, s2
	s_cbranch_scc1 .Lgemm_head_540
	s_barrier
	s_add_i32 s2, s24, s9
	s_lshl_b32 s2, s2, 1
	v_readfirstlane_b32 s3, v153
	s_addk_i32 s2, 0xff80
	s_mov_b32 s6, s70
	s_mov_b32 s7, s71
	s_mov_b32 m0, s3
	v_readfirstlane_b32 s3, v151
	ds_read_b128 v[140:143], v156
	ds_read_b128 v[146:149], v156 offset:1024
	ds_read_b128 v[158:161], v156 offset:2048
	ds_read_b128 v[162:165], v156 offset:3072
	ds_read_b128 v[166:169], v135
	ds_read_b128 v[170:173], v135 offset:1024
	ds_read_b128 v[174:177], v134
	ds_read_b128 v[178:181], v134 offset:1024
	ds_read_b128 v[182:185], v133
	ds_read_b128 v[186:189], v133 offset:1024
	ds_read_b128 v[190:193], v132
	ds_read_b128 v[194:197], v132 offset:1024
	buffer_load_dwordx4 v136, s[4:7], s2 offen lds
	s_add_i32 s2, s2, s8
	s_mov_b32 m0, s3
	s_nop 0
	buffer_load_dwordx4 v136, s[4:7], s2 offen lds
	s_barrier
	s_waitcnt lgkmcnt(0)
	s_setprio 1
	s_waitcnt lgkmcnt(7)
	v_mfma_f32_16x16x32_bf16 v[126:129], v[140:143], v[166:169], v[126:129]
	v_mfma_f32_16x16x32_bf16 v[122:125], v[158:161], v[166:169], v[122:125]
	s_waitcnt lgkmcnt(3)
	v_mfma_f32_16x16x32_bf16 v[110:113], v[140:143], v[182:185], v[110:113]
	v_mfma_f32_16x16x32_bf16 v[106:109], v[158:161], v[182:185], v[106:109]
	v_mfma_f32_16x16x32_bf16 v[126:129], v[146:149], v[170:173], v[126:129]
	v_mfma_f32_16x16x32_bf16 v[122:125], v[162:165], v[170:173], v[122:125]
	v_mfma_f32_16x16x32_bf16 v[118:121], v[140:143], v[174:177], v[118:121]
	v_mfma_f32_16x16x32_bf16 v[114:117], v[158:161], v[174:177], v[114:117]
	s_waitcnt lgkmcnt(2)
	v_mfma_f32_16x16x32_bf16 v[110:113], v[146:149], v[186:189], v[110:113]
	v_mfma_f32_16x16x32_bf16 v[106:109], v[162:165], v[186:189], v[106:109]
	s_waitcnt lgkmcnt(1)
	v_mfma_f32_16x16x32_bf16 v[102:105], v[140:143], v[190:193], v[102:105]
	v_mfma_f32_16x16x32_bf16 v[98:101], v[158:161], v[190:193], v[98:101]
	v_mfma_f32_16x16x32_bf16 v[150:153], v[146:149], v[178:181], v[118:121]
	v_mfma_f32_16x16x32_bf16 v[198:201], v[162:165], v[178:181], v[114:117]
	s_waitcnt lgkmcnt(0)
	v_mfma_f32_16x16x32_bf16 v[202:205], v[146:149], v[194:197], v[102:105]
	v_mfma_f32_16x16x32_bf16 v[236:239], v[162:165], v[194:197], v[98:101]
	s_setprio 0
	s_barrier
	s_nop 0
	ds_read_b128 v[98:101], v155
	ds_read_b128 v[102:105], v155 offset:1024
	ds_read_b128 v[114:117], v155 offset:2048
	ds_read_b128 v[118:121], v155 offset:3072
	s_barrier
; #define WAIT_V(n) asm volatile("s_waitcnt vmcnt(" #n ")" ::: "memory")
; #define WAIT_L(n) asm volatile("s_waitcnt lgkmcnt(" #n ")" ::: "memory")
; #define BAR __builtin_amdgcn_s_barrier()
; template <int MODE>
; __device__ __forceinline__ void gemm_tile(const int ph, const int which, const int pm, const int pn) {
;     ...
;     LDB(B1, 0, 1); BAR; WAIT_L(0); MMA(0, 1, At, B1); BAR;
;     LDA(At, 0, 1); WAIT_V(4); BAR; WAIT_L(0); MMA(1, 0, At, B0); MMA(1, 1, At, B1); BAR;
;   }
;   {
;     LDB(B0, 1, 0); LDA(At, 1, 0); WAIT_V(2); BAR; WAIT_L(0); MMA(0, 0, At, B0); BAR;
	s_waitcnt lgkmcnt(0)
	s_setprio 1
	s_waitcnt lgkmcnt(3)
	v_mfma_f32_16x16x32_bf16 v[94:97], v[98:101], v[166:169], v[94:97]
	s_waitcnt lgkmcnt(1)
	v_mfma_f32_16x16x32_bf16 v[90:93], v[114:117], v[166:169], v[90:93]
	v_mfma_f32_16x16x32_bf16 v[78:81], v[98:101], v[182:185], v[78:81]
	v_mfma_f32_16x16x32_bf16 v[74:77], v[114:117], v[182:185], v[74:77]
	v_mfma_f32_16x16x32_bf16 v[70:73], v[98:101], v[190:193], v[70:73]
	v_mfma_f32_16x16x32_bf16 v[66:69], v[114:117], v[190:193], v[66:69]
	v_mfma_f32_16x16x32_bf16 v[94:97], v[102:105], v[170:173], v[94:97]
	s_waitcnt lgkmcnt(0)
	v_mfma_f32_16x16x32_bf16 v[90:93], v[118:121], v[170:173], v[90:93]
	v_mfma_f32_16x16x32_bf16 v[86:89], v[98:101], v[174:177], v[86:89]
	v_mfma_f32_16x16x32_bf16 v[82:85], v[114:117], v[174:177], v[82:85]
	v_mfma_f32_16x16x32_bf16 v[78:81], v[102:105], v[186:189], v[78:81]
	v_mfma_f32_16x16x32_bf16 v[74:77], v[118:121], v[186:189], v[74:77]
	v_mfma_f32_16x16x32_bf16 v[70:73], v[102:105], v[194:197], v[70:73]
	v_mfma_f32_16x16x32_bf16 v[66:69], v[118:121], v[194:197], v[66:69]
	v_mfma_f32_16x16x32_bf16 v[154:157], v[102:105], v[178:181], v[86:89]
	v_mfma_f32_16x16x32_bf16 v[166:169], v[118:121], v[178:181], v[82:85]
	s_setprio 0
	s_barrier
	s_nop 0
	ds_read_b128 v[82:85], v135 offset:16384
	ds_read_b128 v[86:89], v135 offset:17408
	ds_read_b128 v[170:173], v134 offset:16384
	ds_read_b128 v[174:177], v134 offset:17408
	ds_read_b128 v[178:181], v133 offset:16384
	ds_read_b128 v[182:185], v133 offset:17408
	ds_read_b128 v[186:189], v132 offset:16384
	ds_read_b128 v[190:193], v132 offset:17408
	s_waitcnt vmcnt(4)
	s_barrier
	s_waitcnt lgkmcnt(0)
	s_setprio 1
	s_waitcnt lgkmcnt(7)
	v_mfma_f32_16x16x32_bf16 v[62:65], v[140:143], v[82:85], v[62:65]
	s_waitcnt lgkmcnt(3)
	v_mfma_f32_16x16x32_bf16 v[46:49], v[140:143], v[178:181], v[46:49]
	v_mfma_f32_16x16x32_bf16 v[42:45], v[158:161], v[178:181], v[42:45]
	v_mfma_f32_16x16x32_bf16 v[62:65], v[146:149], v[86:89], v[62:65]
	v_mfma_f32_16x16x32_bf16 v[58:61], v[158:161], v[82:85], v[58:61]
	v_mfma_f32_16x16x32_bf16 v[54:57], v[140:143], v[170:173], v[54:57]
	v_mfma_f32_16x16x32_bf16 v[50:53], v[158:161], v[170:173], v[50:53]
	s_waitcnt lgkmcnt(2)
	v_mfma_f32_16x16x32_bf16 v[46:49], v[146:149], v[182:185], v[46:49]
	v_mfma_f32_16x16x32_bf16 v[42:45], v[162:165], v[182:185], v[42:45]
	s_waitcnt lgkmcnt(1)
	v_mfma_f32_16x16x32_bf16 v[38:41], v[140:143], v[186:189], v[38:41]
	v_mfma_f32_16x16x32_bf16 v[34:37], v[158:161], v[186:189], v[34:37]
	v_mfma_f32_16x16x32_bf16 v[194:197], v[162:165], v[86:89], v[58:61]
	v_mfma_f32_16x16x32_bf16 v[240:243], v[146:149], v[174:177], v[54:57]
	v_mfma_f32_16x16x32_bf16 v[244:247], v[162:165], v[174:177], v[50:53]
	s_waitcnt lgkmcnt(0)
	v_mfma_f32_16x16x32_bf16 v[140:143], v[146:149], v[190:193], v[38:41]
	v_mfma_f32_16x16x32_bf16 v[146:149], v[162:165], v[190:193], v[34:37]
	s_setprio 0
	s_setprio 1
	v_mfma_f32_16x16x32_bf16 v[30:33], v[98:101], v[82:85], v[30:33]
	v_mfma_f32_16x16x32_bf16 v[26:29], v[114:117], v[82:85], v[26:29]
	v_mfma_f32_16x16x32_bf16 v[14:17], v[98:101], v[178:181], v[14:17]
	v_mfma_f32_16x16x32_bf16 v[10:13], v[114:117], v[178:181], v[10:13]
	v_mfma_f32_16x16x32_bf16 v[30:33], v[102:105], v[86:89], v[30:33]
	v_mfma_f32_16x16x32_bf16 v[26:29], v[118:121], v[86:89], v[26:29]
	v_mfma_f32_16x16x32_bf16 v[22:25], v[98:101], v[170:173], v[22:25]
	v_mfma_f32_16x16x32_bf16 v[18:21], v[114:117], v[170:173], v[18:21]
	v_mfma_f32_16x16x32_bf16 v[14:17], v[102:105], v[182:185], v[14:17]
	v_mfma_f32_16x16x32_bf16 v[10:13], v[118:121], v[182:185], v[10:13]
	v_mfma_f32_16x16x32_bf16 v[6:9], v[98:101], v[186:189], v[6:9]
	v_mfma_f32_16x16x32_bf16 v[2:5], v[114:117], v[186:189], v[2:5]
	v_mfma_f32_16x16x32_bf16 v[158:161], v[102:105], v[174:177], v[22:25]
	v_mfma_f32_16x16x32_bf16 v[162:165], v[118:121], v[174:177], v[18:21]
	v_mfma_f32_16x16x32_bf16 v[170:173], v[102:105], v[190:193], v[6:9]
	v_mfma_f32_16x16x32_bf16 v[174:177], v[118:121], v[190:193], v[2:5]
	s_setprio 0
	s_barrier
	s_nop 1
	ds_read_b128 v[2:5], v144
	ds_read_b128 v[6:9], v144 offset:1024
	ds_read_b128 v[178:181], v144 offset:2048
	ds_read_b128 v[182:185], v144 offset:3072
	ds_read_b128 v[18:21], v135 offset:32768
	ds_read_b128 v[22:25], v135 offset:33792
	ds_read_b128 v[34:37], v134 offset:32768
	ds_read_b128 v[38:41], v134 offset:33792
	ds_read_b128 v[58:61], v133 offset:32768
	ds_read_b128 v[186:189], v133 offset:33792
	ds_read_b128 v[190:193], v132 offset:32768
	ds_read_b128 v[248:251], v132 offset:33792
	s_waitcnt vmcnt(2)
	s_barrier
	s_waitcnt lgkmcnt(0)
	s_setprio 1
	s_waitcnt lgkmcnt(7)
	v_mfma_f32_16x16x32_bf16 v[50:53], v[2:5], v[18:21], v[126:129]
	s_waitcnt lgkmcnt(6)
	v_mfma_f32_16x16x32_bf16 v[114:117], v[6:9], v[22:25], v[50:53]
	v_mfma_f32_16x16x32_bf16 v[50:53], v[178:181], v[18:21], v[122:125]
	v_mfma_f32_16x16x32_bf16 v[118:121], v[182:185], v[22:25], v[50:53]
	s_waitcnt lgkmcnt(5)
	v_mfma_f32_16x16x32_bf16 v[50:53], v[2:5], v[34:37], v[150:153]
	s_waitcnt lgkmcnt(4)
	v_mfma_f32_16x16x32_bf16 v[98:101], v[6:9], v[38:41], v[50:53]
	v_mfma_f32_16x16x32_bf16 v[50:53], v[178:181], v[34:37], v[198:201]
	v_mfma_f32_16x16x32_bf16 v[102:105], v[182:185], v[38:41], v[50:53]
	s_waitcnt lgkmcnt(3)
	v_mfma_f32_16x16x32_bf16 v[50:53], v[2:5], v[58:61], v[110:113]
	s_waitcnt lgkmcnt(2)
	v_mfma_f32_16x16x32_bf16 v[82:85], v[6:9], v[186:189], v[50:53]
	v_mfma_f32_16x16x32_bf16 v[50:53], v[178:181], v[58:61], v[106:109]
	v_mfma_f32_16x16x32_bf16 v[86:89], v[182:185], v[186:189], v[50:53]
	s_waitcnt lgkmcnt(1)
	v_mfma_f32_16x16x32_bf16 v[50:53], v[2:5], v[190:193], v[202:205]
	v_mfma_f32_16x16x32_bf16 v[54:57], v[178:181], v[190:193], v[236:239]
	s_waitcnt lgkmcnt(0)
	v_mfma_f32_16x16x32_bf16 v[50:53], v[6:9], v[248:251], v[50:53]
	v_mfma_f32_16x16x32_bf16 v[54:57], v[182:185], v[248:251], v[54:57]
	s_setprio 0
	s_barrier
; #define WAIT_V(n) asm volatile("s_waitcnt vmcnt(" #n ")" ::: "memory")
; #define WAIT_L(n) asm volatile("s_waitcnt lgkmcnt(" #n ")" ::: "memory")
; #define BAR __builtin_amdgcn_s_barrier()
; template <int MODE>
; __device__ __forceinline__ void gemm_tile(const int ph, const int which, const int pm, const int pn) {
;     ...
;     LDB(B0, 1, 0); LDA(At, 1, 0); WAIT_V(2); BAR; WAIT_L(0); MMA(0, 0, At, B0); BAR;
;     LDB(B1, 1, 1); WAIT_V(0); BAR; WAIT_L(0); MMA(0, 1, At, B1); BAR;
;     LDA(At, 1, 1); BAR; WAIT_L(0); MMA(1, 0, At, B0); MMA(1, 1, At, B1); BAR;
;   }
;   if (wr == 0) BAR;
;   bf16_t* C; bf16_t* C2; const float* scale; const float* cw; const float* cb; int ldc, act, browC, ecol;
;   {
;     int ph2 = ph;
;     asm volatile("" : "+s"(ph2));
;     const Params p = load_params();
;     const GD g = make_gd(p, ph2, which);
;     TileP tp; TileE te;
;     tile_setup(g, pm, pn, tp, te);
;     C = te.C; C2 = te.C2; scale = te.scale; cw = te.cw; cb = te.cb; ldc = te.ldc; act = te.act; browC = te.browC; ecol = te.bcol;
;   }
	ds_read_b128 v[150:153], v138
	ds_read_b128 v[198:201], v138 offset:1024
	ds_read_b128 v[202:205], v138 offset:2048
	ds_read_b128 v[136:139], v138 offset:3072
	s_waitcnt vmcnt(0)
	s_barrier
	s_waitcnt lgkmcnt(0)
	s_setprio 1
	s_waitcnt lgkmcnt(3)
	v_mfma_f32_16x16x32_bf16 v[94:97], v[150:153], v[18:21], v[94:97]
	s_waitcnt lgkmcnt(1)
	v_mfma_f32_16x16x32_bf16 v[18:21], v[202:205], v[18:21], v[90:93]
	s_waitcnt lgkmcnt(0)
	v_mfma_f32_16x16x32_bf16 v[126:129], v[136:139], v[22:25], v[18:21]
	v_mfma_f32_16x16x32_bf16 v[18:21], v[150:153], v[34:37], v[154:157]
	v_mfma_f32_16x16x32_bf16 v[106:109], v[198:201], v[38:41], v[18:21]
	v_mfma_f32_16x16x32_bf16 v[18:21], v[202:205], v[34:37], v[166:169]
	v_mfma_f32_16x16x32_bf16 v[110:113], v[136:139], v[38:41], v[18:21]
	v_mfma_f32_16x16x32_bf16 v[18:21], v[150:153], v[58:61], v[78:81]
	v_mfma_f32_16x16x32_bf16 v[90:93], v[198:201], v[186:189], v[18:21]
	v_mfma_f32_16x16x32_bf16 v[18:21], v[202:205], v[58:61], v[74:77]
	v_mfma_f32_16x16x32_bf16 v[122:125], v[198:201], v[22:25], v[94:97]
	v_mfma_f32_16x16x32_bf16 v[94:97], v[136:139], v[186:189], v[18:21]
	v_mfma_f32_16x16x32_bf16 v[18:21], v[150:153], v[190:193], v[70:73]
	v_mfma_f32_16x16x32_bf16 v[74:77], v[198:201], v[248:251], v[18:21]
	v_mfma_f32_16x16x32_bf16 v[18:21], v[202:205], v[190:193], v[66:69]
	v_mfma_f32_16x16x32_bf16 v[78:81], v[136:139], v[248:251], v[18:21]
	s_setprio 0
	s_barrier
	ds_read_b128 v[70:73], v135 offset:49152
	ds_read_b128 v[154:157], v135 offset:50176
	ds_read_b128 v[166:169], v134 offset:49152
	ds_read_b128 v[186:189], v134 offset:50176
	ds_read_b128 v[190:193], v133 offset:49152
	ds_read_b128 v[236:239], v133 offset:50176
	ds_read_b128 v[248:251], v132 offset:49152
	ds_read_b128 v[132:135], v132 offset:50176
	s_barrier
	s_waitcnt lgkmcnt(0)
	s_setprio 1
	s_waitcnt lgkmcnt(7)
	v_mfma_f32_16x16x32_bf16 v[18:21], v[2:5], v[70:73], v[62:65]
	s_waitcnt lgkmcnt(6)
	v_mfma_f32_16x16x32_bf16 v[58:61], v[6:9], v[154:157], v[18:21]
	v_mfma_f32_16x16x32_bf16 v[18:21], v[178:181], v[70:73], v[194:197]
	v_mfma_f32_16x16x32_bf16 v[62:65], v[182:185], v[154:157], v[18:21]
	s_waitcnt lgkmcnt(5)
	v_mfma_f32_16x16x32_bf16 v[18:21], v[2:5], v[166:169], v[240:243]
	s_waitcnt lgkmcnt(4)
	v_mfma_f32_16x16x32_bf16 v[34:37], v[6:9], v[186:189], v[18:21]
	v_mfma_f32_16x16x32_bf16 v[18:21], v[178:181], v[166:169], v[244:247]
	v_mfma_f32_16x16x32_bf16 v[38:41], v[182:185], v[186:189], v[18:21]
	s_waitcnt lgkmcnt(3)
	v_mfma_f32_16x16x32_bf16 v[18:21], v[2:5], v[190:193], v[46:49]
	s_waitcnt lgkmcnt(1)
	v_mfma_f32_16x16x32_bf16 v[2:5], v[2:5], v[248:251], v[140:143]
	v_mfma_f32_16x16x32_bf16 v[18:21], v[6:9], v[236:239], v[18:21]
	v_mfma_f32_16x16x32_bf16 v[22:25], v[178:181], v[190:193], v[42:45]
	s_waitcnt lgkmcnt(0)
	v_mfma_f32_16x16x32_bf16 v[2:5], v[6:9], v[132:135], v[2:5]
	v_mfma_f32_16x16x32_bf16 v[6:9], v[178:181], v[248:251], v[146:149]
	v_mfma_f32_16x16x32_bf16 v[22:25], v[182:185], v[236:239], v[22:25]
	v_mfma_f32_16x16x32_bf16 v[6:9], v[182:185], v[132:135], v[6:9]
	s_setprio 0
	s_setprio 1
	v_mfma_f32_16x16x32_bf16 v[26:29], v[202:205], v[70:73], v[26:29]
	v_mfma_f32_16x16x32_bf16 v[30:33], v[150:153], v[70:73], v[30:33]
	v_mfma_f32_16x16x32_bf16 v[70:73], v[136:139], v[154:157], v[26:29]
	v_mfma_f32_16x16x32_bf16 v[26:29], v[150:153], v[166:169], v[158:161]
	v_mfma_f32_16x16x32_bf16 v[42:45], v[198:201], v[186:189], v[26:29]
	v_mfma_f32_16x16x32_bf16 v[26:29], v[202:205], v[166:169], v[162:165]
	v_mfma_f32_16x16x32_bf16 v[14:17], v[150:153], v[190:193], v[14:17]
	v_mfma_f32_16x16x32_bf16 v[10:13], v[202:205], v[190:193], v[10:13]
	v_mfma_f32_16x16x32_bf16 v[66:69], v[198:201], v[154:157], v[30:33]
	v_mfma_f32_16x16x32_bf16 v[46:49], v[136:139], v[186:189], v[26:29]
	v_mfma_f32_16x16x32_bf16 v[26:29], v[198:201], v[236:239], v[14:17]
	v_mfma_f32_16x16x32_bf16 v[30:33], v[136:139], v[236:239], v[10:13]
	v_mfma_f32_16x16x32_bf16 v[10:13], v[150:153], v[248:251], v[170:173]
	v_mfma_f32_16x16x32_bf16 v[14:17], v[202:205], v[248:251], v[174:177]
	v_mfma_f32_16x16x32_bf16 v[10:13], v[198:201], v[132:135], v[10:13]
	v_mfma_f32_16x16x32_bf16 v[14:17], v[136:139], v[132:135], v[14:17]
	s_setprio 0
	s_load_dwordx4 s[4:7], s[0:1], 0xf0
	s_movk_i32 s2, 0x100
	v_cmp_gt_u32_e32 vcc, s2, v0
	s_barrier
	s_and_saveexec_b64 s[2:3], vcc
	s_cbranch_execz .LBB0_543
	s_barrier
.LBB0_543:
	s_or_b64 exec, exec, s[2:3]
	s_mov_b32 s21, s34
	s_mov_b64 s[2:3], s[0:1]
	s_mov_b64 s[10:11], -1
	s_mov_b64 s[2:3], 0
	s_mov_b64 s[8:9], 0
	s_waitcnt lgkmcnt(0)
	s_add_u32 s19, s6, 0xe1a6000
	s_addc_u32 s20, s7, 0
	s_cmp_lt_i32 s21, 3
	s_cbranch_scc1 .LBB0_552
	s_cmp_gt_i32 s21, 16
	s_cbranch_scc0 .LBB0_546
	s_cmp_lg_u32 s21, 17
	s_mov_b64 s[10:11], 0
	s_cselect_b64 s[8:9], -1, 0
